# RWKV coefficient pass on matrix cores; GDN staging pre-scales V by beta and stores -beta*eg so the serial loop drops 8 multiplies per 4-token group
# baseline (speedup 1.0000x reference)
.LBB0_539:
	s_or_b64 exec, exec, s[0:1]
	v_bfe_u32 v25, v112, 1, 4
	v_subrev_co_u32_e32 v27, vcc, 10, v25
	s_xor_b64 s[4:5], vcc, -1
	s_waitcnt lgkmcnt(0)
	s_barrier
	v_and_b32_e32 v150, 15, v180
	v_bfe_u32 v151, v180, 4, 2
	v_lshrrev_b32_e32 v152, 6, v180
	v_and_b32_e32 v157, 7, v150
	v_lshl_add_u32 v153, v152, 3, v157
	v_mul_u32_u24_e32 v153, 0x210, v153
	v_lshl_add_u32 v133, v151, 4, v153
	v_and_b32_e32 v154, 8, v150
	v_sub_u32_e32 v154, 8, v154
	v_mul_u32_u24_e32 v154, 0x1080, v154
	v_add_u32_e32 v132, v133, v154
	v_add_u32_e32 v133, 0x8400, v133
	ds_read_b128 v[30:33], v132 offset:0
	ds_read_b128 v[62:65], v133 offset:0
	ds_read_b128 v[34:37], v132 offset:64
	ds_read_b128 v[66:69], v133 offset:64
	ds_read_b128 v[38:41], v132 offset:128
	ds_read_b128 v[70:73], v133 offset:128
	ds_read_b128 v[42:45], v132 offset:192
	ds_read_b128 v[74:77], v133 offset:192
	ds_read_b128 v[46:49], v132 offset:256
	ds_read_b128 v[78:81], v133 offset:256
	ds_read_b128 v[50:53], v132 offset:320
	ds_read_b128 v[82:85], v133 offset:320
	ds_read_b128 v[54:57], v132 offset:384
	ds_read_b128 v[86:89], v133 offset:384
	ds_read_b128 v[58:61], v132 offset:448
	ds_read_b128 v[90:93], v133 offset:448
	v_lshrrev_b32_e32 v155, 1, v151
	v_and_b32_e32 v156, 1, v151
	v_lshl_add_u32 v153, v152, 1, v156
	v_lshlrev_b32_e32 v135, 4, v153
	v_add_u32_e32 v137, 0x21900, v135
	v_add_u32_e32 v135, 0x21800, v135
	v_lshl_add_u32 v136, v152, 3, v157
	v_lshlrev_b32_e32 v136, 2, v136
	v_add_u32_e32 v136, 0x21800, v136
	ds_read_b128 v[140:143], v135
	ds_read_b128 v[144:147], v137
	ds_read_b32 v148, v136
	v_lshl_add_u32 v134, v152, 1, v155
	v_lshlrev_b32_e32 v134, 8, v134
	v_lshl_add_u32 v134, v156, 7, v134
	v_lshl_add_u32 v134, v157, 2, v134
	v_add_u32_e32 v134, 0x14800, v134
	v_lshrrev_b32_e32 v153, 2, v157
	v_cmp_eq_u32_e32 vcc, v156, v153
	v_and_b32_e32 v158, 3, v157
	v_sub_u32_e32 v154, 1, v155
	v_add_u32_e32 v158, v158, v154
	v_mov_b32_e32 v154, 99
	v_cndmask_b32_e32 v158, v154, v158, vcc
	v_cmp_gt_u32_e32 vcc, v156, v153
	v_mov_b32_e32 v160, 1.0
	s_nop 1
	v_cndmask_b32_e32 v159, 0, v160, vcc
	v_cmp_eq_u32_e64 s[80:81], 1, v155
	v_cmp_ge_u32_e64 s[0:1], 1, v158
	v_cmp_ge_u32_e64 s[4:5], 2, v158
	v_cmp_ge_u32_e64 s[6:7], 3, v158
	v_cmp_ge_u32_e32 vcc, 0, v158
	s_waitcnt lgkmcnt(0)
	v_mfma_f32_16x16x4_f32 v[96:99], v30, v62, 0
	v_mfma_f32_16x16x4_f32 v[100:103], v31, v63, 0
	v_mfma_f32_16x16x4_f32 v[96:99], v32, v64, v[96:99]
	v_mfma_f32_16x16x4_f32 v[100:103], v33, v65, v[100:103]
	v_sub_f32_e32 v164, v140, v148
	v_sub_f32_e32 v165, v141, v148
	v_sub_f32_e32 v166, v142, v148
	v_sub_f32_e32 v167, v143, v148
	v_min_f32_e32 v164, 0, v164
	v_min_f32_e32 v165, 0, v165
	v_min_f32_e32 v166, 0, v166
	v_min_f32_e32 v167, 0, v167
	v_mul_f32_e32 v164, 0x3fb8aa3b, v164
	v_mul_f32_e32 v165, 0x3fb8aa3b, v165
	v_mul_f32_e32 v166, 0x3fb8aa3b, v166
	v_mul_f32_e32 v167, 0x3fb8aa3b, v167
	v_exp_f32_e32 v164, v164
	v_exp_f32_e32 v165, v165
	v_exp_f32_e32 v166, v166
	v_exp_f32_e32 v167, v167
	v_mfma_f32_16x16x4_f32 v[96:99], v34, v66, v[96:99]
	v_mfma_f32_16x16x4_f32 v[100:103], v35, v67, v[100:103]
	v_mfma_f32_16x16x4_f32 v[96:99], v36, v68, v[96:99]
	v_mfma_f32_16x16x4_f32 v[100:103], v37, v69, v[100:103]
	v_cndmask_b32_e64 v144, v144, v160, s[80:81]
	v_cndmask_b32_e64 v145, v145, v160, s[80:81]
	v_cndmask_b32_e64 v146, v146, v160, s[80:81]
	v_cndmask_b32_e64 v147, v147, v160, s[80:81]
	v_mul_f32_e32 v164, v164, v144
	v_mul_f32_e32 v165, v165, v145
	v_mul_f32_e32 v166, v166, v146
	v_mul_f32_e32 v167, v167, v147
	v_cndmask_b32_e32 v164, v159, v164, vcc
	v_cndmask_b32_e64 v165, v159, v165, s[0:1]
	v_cndmask_b32_e64 v166, v159, v166, s[4:5]
	v_cndmask_b32_e64 v167, v159, v167, s[6:7]
	v_mfma_f32_16x16x4_f32 v[96:99], v38, v70, v[96:99]
	v_mfma_f32_16x16x4_f32 v[100:103], v39, v71, v[100:103]
	v_mfma_f32_16x16x4_f32 v[96:99], v40, v72, v[96:99]
	v_mfma_f32_16x16x4_f32 v[100:103], v41, v73, v[100:103]
	v_mfma_f32_16x16x4_f32 v[96:99], v42, v74, v[96:99]
	v_mfma_f32_16x16x4_f32 v[100:103], v43, v75, v[100:103]
	v_mfma_f32_16x16x4_f32 v[96:99], v44, v76, v[96:99]
	v_mfma_f32_16x16x4_f32 v[100:103], v45, v77, v[100:103]
	v_mfma_f32_16x16x4_f32 v[96:99], v46, v78, v[96:99]
	v_mfma_f32_16x16x4_f32 v[100:103], v47, v79, v[100:103]
	v_mfma_f32_16x16x4_f32 v[96:99], v48, v80, v[96:99]
	v_mfma_f32_16x16x4_f32 v[100:103], v49, v81, v[100:103]
	v_mfma_f32_16x16x4_f32 v[96:99], v50, v82, v[96:99]
	v_mfma_f32_16x16x4_f32 v[100:103], v51, v83, v[100:103]
	v_mfma_f32_16x16x4_f32 v[96:99], v52, v84, v[96:99]
	v_mfma_f32_16x16x4_f32 v[100:103], v53, v85, v[100:103]
	v_mfma_f32_16x16x4_f32 v[96:99], v54, v86, v[96:99]
	v_mfma_f32_16x16x4_f32 v[100:103], v55, v87, v[100:103]
	v_mfma_f32_16x16x4_f32 v[96:99], v56, v88, v[96:99]
	v_mfma_f32_16x16x4_f32 v[100:103], v57, v89, v[100:103]
	v_mfma_f32_16x16x4_f32 v[96:99], v58, v90, v[96:99]
	v_mfma_f32_16x16x4_f32 v[100:103], v59, v91, v[100:103]
	v_mfma_f32_16x16x4_f32 v[96:99], v60, v92, v[96:99]
	v_mfma_f32_16x16x4_f32 v[100:103], v61, v93, v[100:103]
	s_nop 7
	s_nop 2
	v_pk_add_f32 v[96:97], v[96:97], v[100:101]
	v_pk_add_f32 v[98:99], v[98:99], v[102:103]
	v_mul_f32_e32 v96, v96, v164
	v_mul_f32_e32 v97, v97, v165
	v_mul_f32_e32 v98, v98, v166
	v_mul_f32_e32 v99, v99, v167
	ds_write_b32 v134, v96 offset:0
	ds_write_b32 v134, v97 offset:32
	ds_write_b32 v134, v98 offset:64
	ds_write_b32 v134, v99 offset:96
	v_and_b32_e32 v153, 63, v180
	v_lshlrev_b32_e32 v138, 11, v152
	v_lshl_add_u32 v138, v153, 2, v138
	v_add_u32_e32 v138, 0x10800, v138
	v_lshlrev_b32_e32 v139, 5, v152
	v_add_u32_e32 v139, 0x21800, v139
	ds_read_b32 v30, v138 offset:0
	ds_read_b32 v31, v138 offset:256
	ds_read_b32 v32, v138 offset:512
	ds_read_b32 v33, v138 offset:768
	ds_read_b32 v34, v138 offset:1024
	ds_read_b32 v35, v138 offset:1280
	ds_read_b32 v36, v138 offset:1536
	ds_read_b32 v37, v138 offset:1792
	ds_read_b128 v[40:43], v139 offset:256
	ds_read_b128 v[44:47], v139 offset:272
	ds_read_b128 v[48:51], v139 offset:512
	ds_read_b128 v[52:55], v139 offset:528
	s_waitcnt lgkmcnt(0)
	v_mul_f32_e32 v30, v40, v30
	v_mul_f32_e32 v31, v41, v31
	v_mul_f32_e32 v32, v42, v32
	v_mul_f32_e32 v33, v43, v33
	v_mul_f32_e32 v34, v44, v34
	v_mul_f32_e32 v35, v45, v35
	v_mul_f32_e32 v36, v46, v36
	v_mul_f32_e32 v37, v47, v37
	v_mul_f32_e64 v48, -v40, v48
	v_mul_f32_e64 v49, -v41, v49
	v_mul_f32_e64 v50, -v42, v50
	v_mul_f32_e64 v51, -v43, v51
	v_mul_f32_e64 v52, -v44, v52
	v_mul_f32_e64 v53, -v45, v53
	v_mul_f32_e64 v54, -v46, v54
	v_mul_f32_e64 v55, -v47, v55
	ds_write_b32 v138, v30 offset:0
	ds_write_b32 v138, v31 offset:256
	ds_write_b32 v138, v32 offset:512
	ds_write_b32 v138, v33 offset:768
	ds_write_b32 v138, v34 offset:1024
	ds_write_b32 v138, v35 offset:1280
	ds_write_b32 v138, v36 offset:1536
	ds_write_b32 v138, v37 offset:1792
	ds_write_b128 v139, v[48:51]
	ds_write_b128 v139, v[52:55] offset:16
	s_lshl_b32 s0, s17, 6
	s_add_i32 s72, s0, s16
	v_and_b32_e32 v128, 63, v112
	s_cmp_eq_u32 s17, 31
	s_waitcnt lgkmcnt(0)
	s_barrier
	s_cbranch_scc1 .LBB0_549
	s_add_i32 s0, s72, 64
	s_mov_b32 s1, s73
	v_ashrrev_i32_e32 v27, 31, v26
	v_lshlrev_b32_e32 v2, 1, v23
	v_mov_b32_e32 v3, v94
	v_ashrrev_i32_e32 v23, 31, v22
	v_ashrrev_i32_e32 v25, 31, v24
	v_lshl_add_u64 v[18:19], s[0:1], 0, v[26:27]
	v_mov_b64_e32 v[20:21], s[12:13]
	v_lshl_add_u64 v[10:11], s[8:9], 0, v[2:3]
	v_lshl_add_u64 v[2:3], s[0:1], 0, v[22:23]
	v_lshl_add_u64 v[12:13], s[0:1], 0, v[24:25]
	v_mad_u64_u32 v[20:21], s[4:5], v18, s83, v[20:21]
	v_mad_u64_u32 v[6:7], s[4:5], v2, s83, v[10:11]
	v_mad_u64_u32 v[14:15], s[4:5], v12, s83, v[10:11]
	v_mad_i32_i24 v21, v19, s83, v21
	v_lshlrev_b32_e32 v18, 1, v28
	v_mov_b32_e32 v19, v94
	v_mad_i32_i24 v7, v3, s83, v7
	v_mad_i32_i24 v15, v13, s83, v15
	v_lshl_add_u64 v[18:19], v[20:21], 0, v[18:19]
	v_or_b32_e32 v22, s0, v128
	v_mov_b64_e32 v[20:21], s[14:15]
	global_load_dwordx4 v[2:5], v[6:7], off
	s_nop 0
	global_load_dwordx4 v[6:9], v[6:7], off offset:1024
	s_nop 0
	global_load_dwordx4 v[10:13], v[14:15], off
	s_nop 0
	global_load_dwordx4 v[14:17], v[14:15], off offset:1024
	v_mad_u64_u32 v[22:23], s[0:1], v22, s87, v[20:21]
	global_load_dwordx4 v[18:21], v[18:19], off offset:2048
	s_nop 0
	global_load_dword v126, v[22:23], off offset:512
	global_load_dword v127, v[22:23], off offset:528
.LBB0_549:
	v_readfirstlane_b32 s0, v180
	s_nop 1
	s_cmpk_ge_u32 s0, 0x100
	s_cbranch_scc1 .Lgdn_out
	v_and_b32_e32 v166, 15, v180
	v_bfe_u32 v167, v180, 4, 2
	v_lshrrev_b32_e32 v168, 6, v180
	v_and_b32_e32 v177, 3, v166
	v_bfe_u32 v178, v166, 3, 1
	v_lshl_add_u32 v177, v178, 2, v177
	v_mul_u32_u24_e32 v177, 0x210, v177
	v_bfe_u32 v87, v166, 2, 1
	v_lshlrev_b32_e32 v87, 8, v87
	v_and_b32_e32 v178, 3, v166
	v_lshl_add_u32 v87, v178, 5, v87
	v_lshl_add_u32 v87, v167, 2, v87
	v_add_u32_e32 v87, 0x14880, v87
	v_and_b32_e32 v178, 4, v166
	v_sub_u32_e32 v178, 4, v178
	v_mul_u32_u24_e32 v178, 0x2100, v178
	v_lshl_add_u32 v169, v167, 4, v177
	v_add_u32_e32 v169, v169, v178
	v_mul_u32_u24_e32 v177, 0x210, v167
	v_lshl_add_u32 v170, v166, 2, v177
	v_add_u32_e32 v170, 0x8400, v170
	v_add_u32_e32 v237, 0x840, v170
	v_add_u32_e32 v95, 0x1080, v170
	v_lshlrev_b32_e32 v177, 6, v168
	v_lshl_add_u32 v177, v166, 2, v177
	v_add_u32_e32 v171, 0x10800, v177
	v_lshl_add_u32 v172, v167, 8, v177
	v_add_u32_e32 v172, 0x1d800, v172
	v_mov_b32_e32 v173, 0x14800
	v_lshlrev_b32_e32 v174, 5, v167
	v_add_u32_e32 v174, 0x14900, v174
	v_mov_b32_e32 v175, 0x21900
	v_mov_b32_e32 v93, 0x21800
	v_lshl_add_u32 v176, v167, 2, v175
	v_cmp_eq_u32_e32 vcc, 1, v167
	v_cmp_eq_u32_e64 s[4:5], 2, v167
	v_cmp_eq_u32_e64 s[6:7], 3, v167
	s_mov_b32 s40, 1
	s_mov_b32 s41, 0
	v_mov_b32_e32 v91, 0x15800
	v_mov_b32_e32 v92, 1
	ds_read_b128 v[22:25], v169 offset:0
	ds_read_b128 v[26:29], v169 offset:64
	ds_read_b128 v[30:33], v169 offset:128
	ds_read_b128 v[34:37], v169 offset:192
	ds_read_b128 v[38:41], v169 offset:256
	ds_read_b128 v[42:45], v169 offset:320
	ds_read_b128 v[46:49], v169 offset:384
	ds_read_b128 v[50:53], v169 offset:448
	ds_read2_b32 v[54:55], v170 offset0:0 offset1:16
	ds_read2_b32 v[56:57], v170 offset0:32 offset1:48
	ds_read2_b32 v[58:59], v170 offset0:64 offset1:80
	ds_read2_b32 v[60:61], v170 offset0:96 offset1:112
	ds_read2st64_b32 v[70:71], v171 offset0:0 offset1:1
	ds_read2st64_b32 v[72:73], v171 offset0:2 offset1:3
	ds_read_b128 v[132:135], v93 offset:0
	ds_read_b128 v[136:139], v175 offset:256
	ds_read_b32 v151, v176 offset:256
	ds_read_b32 v152, v176 offset:512
	ds_read_b32 v150, v173 offset:32
	ds_read_b64 v[148:149], v173 offset:64
	ds_read_b128 v[140:143], v173 offset:96
	ds_read_b128 v[144:147], v174 offset:0
	s_mov_b32 s1, 0
	s_waitcnt lgkmcnt(0)
	s_waitcnt lgkmcnt(1)
	v_mfma_f32_16x16x4_f32 v[96:99], v22, v184, 0
	v_mfma_f32_16x16x4_f32 v[100:103], v23, v185, 0
	v_mfma_f32_16x16x4_f32 v[96:99], v24, v186, v[96:99]
	v_mfma_f32_16x16x4_f32 v[100:103], v25, v187, v[100:103]
	v_mul_f32_e32 v240, v238, v139
	v_rcp_f32_e32 v89, v240
	v_readfirstlane_b32 s0, v240
	v_mfma_f32_16x16x4_f32 v[96:99], v26, v188, v[96:99]
	v_mfma_f32_16x16x4_f32 v[100:103], v27, v189, v[100:103]
	v_mfma_f32_16x16x4_f32 v[96:99], v28, v190, v[96:99]
	v_mfma_f32_16x16x4_f32 v[100:103], v29, v191, v[100:103]
	ds_read_b32 v86, v87 offset:0
	ds_read2_b32 v[62:63], v237 offset0:0 offset1:16
	ds_read2_b32 v[64:65], v237 offset0:32 offset1:48
	v_mfma_f32_16x16x4_f32 v[96:99], v30, v192, v[96:99]
	v_mfma_f32_16x16x4_f32 v[100:103], v31, v193, v[100:103]
	v_mfma_f32_16x16x4_f32 v[96:99], v32, v194, v[96:99]
	v_mfma_f32_16x16x4_f32 v[100:103], v33, v195, v[100:103]
	ds_read2_b32 v[66:67], v237 offset0:64 offset1:80
	ds_read2_b32 v[68:69], v237 offset0:96 offset1:112
	ds_read2st64_b32 v[74:75], v171 offset0:4 offset1:5
	v_mfma_f32_16x16x4_f32 v[96:99], v34, v196, v[96:99]
	v_mfma_f32_16x16x4_f32 v[100:103], v35, v197, v[100:103]
	v_mfma_f32_16x16x4_f32 v[96:99], v36, v198, v[96:99]
	v_mfma_f32_16x16x4_f32 v[100:103], v37, v199, v[100:103]
	ds_read2st64_b32 v[76:77], v171 offset0:6 offset1:7
	ds_read_b128 v[216:219], v93 offset:16
	ds_read_b128 v[220:223], v175 offset:272
	v_mfma_f32_16x16x4_f32 v[96:99], v38, v200, v[96:99]
	v_mfma_f32_16x16x4_f32 v[100:103], v39, v201, v[100:103]
	v_mfma_f32_16x16x4_f32 v[96:99], v40, v202, v[96:99]
	v_mfma_f32_16x16x4_f32 v[100:103], v41, v203, v[100:103]
	ds_read_b32 v235, v176 offset:272
	ds_read_b32 v236, v176 offset:528
	ds_read_b32 v234, v173 offset:176
	v_mfma_f32_16x16x4_f32 v[96:99], v42, v204, v[96:99]
	v_mfma_f32_16x16x4_f32 v[100:103], v43, v205, v[100:103]
	v_mfma_f32_16x16x4_f32 v[96:99], v44, v206, v[96:99]
	v_mfma_f32_16x16x4_f32 v[100:103], v45, v207, v[100:103]
	ds_read_b64 v[232:233], v173 offset:208
	ds_read_b128 v[224:227], v173 offset:240
	ds_read_b128 v[228:231], v174 offset:144
	v_mfma_f32_16x16x4_f32 v[96:99], v46, v208, v[96:99]
	v_mfma_f32_16x16x4_f32 v[100:103], v47, v209, v[100:103]
	v_mfma_f32_16x16x4_f32 v[96:99], v48, v210, v[96:99]
	v_mfma_f32_16x16x4_f32 v[100:103], v49, v211, v[100:103]
	v_mfma_f32_16x16x4_f32 v[96:99], v50, v212, v[96:99]
	v_mfma_f32_16x16x4_f32 v[100:103], v51, v213, v[100:103]
	v_mfma_f32_16x16x4_f32 v[96:99], v52, v214, v[96:99]
	v_mfma_f32_16x16x4_f32 v[100:103], v53, v215, v[100:103]
	s_nop 7
	s_nop 1
	v_pk_mul_f32 v[100:101], v[100:101], v[238:239] op_sel_hi:[1,0]
	v_pk_mul_f32 v[102:103], v[102:103], v[238:239] op_sel_hi:[1,0]
	v_pk_fma_f32 v[78:79], v[96:97], v[238:239], v[100:101] op_sel_hi:[1,0,1]
	v_pk_fma_f32 v[80:81], v[98:99], v[238:239], v[102:103] op_sel_hi:[1,0,1]
	v_pk_fma_f32 v[96:97], v[96:97], v[238:239], v[100:101] op_sel_hi:[1,0,1]
	v_pk_fma_f32 v[98:99], v[98:99], v[238:239], v[102:103] op_sel_hi:[1,0,1]
	s_nop 0
	v_permlane32_swap_b32_e32 v96, v78
	v_permlane32_swap_b32_e32 v97, v79
	v_permlane32_swap_b32_e32 v98, v80
	v_permlane32_swap_b32_e32 v99, v81
	v_mov_b32_e32 v82, v96
	v_mov_b32_e32 v83, v97
	v_mov_b32_e32 v84, v98
	v_mov_b32_e32 v85, v99
	s_nop 0
	v_permlane16_swap_b32_e32 v96, v82
	v_permlane16_swap_b32_e32 v97, v83
	v_permlane16_swap_b32_e32 v98, v84
	v_permlane16_swap_b32_e32 v99, v85
	v_fma_f32 v108, v132, v96, v70
	v_fma_f32 v109, v133, v97, v71
	v_fma_f32 v110, v134, v98, v72
	v_fma_f32 v111, v135, v99, v73
	v_fma_f32 v109, -v150, v108, v109
	v_fma_f32 v110, -v148, v108, v110
	v_fma_f32 v111, -v140, v108, v111
	v_fma_f32 v110, -v149, v109, v110
	v_fma_f32 v111, -v141, v109, v111
	v_fma_f32 v111, -v142, v110, v111
	v_cndmask_b32_e32 v182, v108, v109, vcc
	v_cndmask_b32_e64 v182, v182, v110, s[4:5]
	v_cndmask_b32_e64 v182, v182, v111, s[6:7]
	v_mul_f32_e32 v182, v152, v182
	s_cmp_lt_u32 s0, 0x2b800000
	s_cbranch_scc0 .Lgdn_nomat_0_0
	v_pk_mul_f32 v[184:185], v[184:185], v[240:241] op_sel_hi:[1,0]
	v_pk_mul_f32 v[186:187], v[186:187], v[240:241] op_sel_hi:[1,0]
	v_pk_mul_f32 v[188:189], v[188:189], v[240:241] op_sel_hi:[1,0]
	v_pk_mul_f32 v[190:191], v[190:191], v[240:241] op_sel_hi:[1,0]
	v_pk_mul_f32 v[192:193], v[192:193], v[240:241] op_sel_hi:[1,0]
	v_pk_mul_f32 v[194:195], v[194:195], v[240:241] op_sel_hi:[1,0]
	v_pk_mul_f32 v[196:197], v[196:197], v[240:241] op_sel_hi:[1,0]
	v_pk_mul_f32 v[198:199], v[198:199], v[240:241] op_sel_hi:[1,0]
	v_pk_mul_f32 v[200:201], v[200:201], v[240:241] op_sel_hi:[1,0]
	v_pk_mul_f32 v[202:203], v[202:203], v[240:241] op_sel_hi:[1,0]
	v_pk_mul_f32 v[204:205], v[204:205], v[240:241] op_sel_hi:[1,0]
	v_pk_mul_f32 v[206:207], v[206:207], v[240:241] op_sel_hi:[1,0]
	v_pk_mul_f32 v[208:209], v[208:209], v[240:241] op_sel_hi:[1,0]
	v_pk_mul_f32 v[210:211], v[210:211], v[240:241] op_sel_hi:[1,0]
	v_pk_mul_f32 v[212:213], v[212:213], v[240:241] op_sel_hi:[1,0]
	v_pk_mul_f32 v[214:215], v[214:215], v[240:241] op_sel_hi:[1,0]
	v_mov_b32_e32 v240, 1.0
	v_mov_b32_e32 v89, 1.0
.Lgdn_nomat_0_0:
	v_mov_b32_e32 v238, v240
	v_mul_f32_e32 v90, v182, v89
	s_nop 1
	v_mfma_f32_16x16x4_f32 v[184:187], v54, v90, v[184:187]
	v_mfma_f32_16x16x4_f32 v[188:191], v55, v90, v[188:191]
	v_mfma_f32_16x16x4_f32 v[192:195], v56, v90, v[192:195]
	v_mfma_f32_16x16x4_f32 v[196:199], v57, v90, v[196:199]
	v_mfma_f32_16x16x4_f32 v[200:203], v58, v90, v[200:203]
	v_mfma_f32_16x16x4_f32 v[204:207], v59, v90, v[204:207]
	v_mfma_f32_16x16x4_f32 v[208:211], v60, v90, v[208:211]
	v_mfma_f32_16x16x4_f32 v[212:215], v61, v90, v[212:215]
	v_pk_mul_f32 v[78:79], v[78:79], v[138:139] op_sel:[0,1] op_sel_hi:[1,1]
	v_pk_mul_f32 v[80:81], v[80:81], v[138:139] op_sel:[0,1] op_sel_hi:[1,1]
	v_cndmask_b32_e32 v183, v82, v83, vcc
	v_cndmask_b32_e64 v183, v183, v84, s[4:5]
	v_cndmask_b32_e64 v183, v183, v85, s[6:7]
	v_mul_f32_e32 v179, v151, v183
	v_fmac_f32_e32 v179, v144, v108
	v_fmac_f32_e32 v179, v145, v109
	v_fmac_f32_e32 v179, v146, v110
	v_fmac_f32_e32 v179, v147, v111
	ds_write_b32 v172, v179 offset:0
	s_waitcnt lgkmcnt(1)
	v_mfma_f32_16x16x4_f32 v[96:99], v86, v182, v[78:81]
	s_nop 7
	v_mul_f32_e32 v240, v238, v223
	v_rcp_f32_e32 v89, v240
	v_readfirstlane_b32 s0, v240
	ds_read_b128 v[22:25], v169 offset:4224
	ds_read_b128 v[26:29], v169 offset:4288
	ds_read_b128 v[30:33], v169 offset:4352
	ds_read_b128 v[34:37], v169 offset:4416
	ds_read_b128 v[38:41], v169 offset:4480
	ds_read_b128 v[42:45], v169 offset:4544
	ds_read_b128 v[46:49], v169 offset:4608
	ds_read_b128 v[50:53], v169 offset:4672
	ds_read2_b32 v[54:55], v95 offset0:0 offset1:16
	ds_read2_b32 v[56:57], v95 offset0:32 offset1:48
	ds_read2_b32 v[58:59], v95 offset0:64 offset1:80
	ds_read2_b32 v[60:61], v95 offset0:96 offset1:112
	ds_read2st64_b32 v[70:71], v171 offset0:8 offset1:9
	ds_read2st64_b32 v[72:73], v171 offset0:10 offset1:11
	ds_read_b128 v[132:135], v93 offset:32
	ds_read_b128 v[136:139], v175 offset:288
	ds_read_b32 v151, v176 offset:288
	ds_read_b32 v152, v176 offset:544
	ds_read_b32 v150, v173 offset:544
	ds_read_b64 v[148:149], v173 offset:576
	ds_read_b128 v[140:143], v173 offset:608
	ds_read_b128 v[144:147], v174 offset:512
	v_mov_b32_e32 v82, v96
	v_mov_b32_e32 v83, v97
	v_mov_b32_e32 v84, v98
	v_mov_b32_e32 v85, v99
	s_nop 0
	v_permlane16_swap_b32_e32 v96, v82
	v_permlane16_swap_b32_e32 v97, v83
	v_permlane16_swap_b32_e32 v98, v84
	v_permlane16_swap_b32_e32 v99, v85
	v_fma_f32 v108, v216, v96, v74
	v_fma_f32 v109, v217, v97, v75
	v_fma_f32 v110, v218, v98, v76
	v_fma_f32 v111, v219, v99, v77
	v_fma_f32 v109, -v234, v108, v109
	v_fma_f32 v110, -v232, v108, v110
	v_fma_f32 v111, -v224, v108, v111
	v_fma_f32 v110, -v233, v109, v110
	v_fma_f32 v111, -v225, v109, v111
	v_fma_f32 v111, -v226, v110, v111
	v_cndmask_b32_e32 v182, v108, v109, vcc
	v_cndmask_b32_e64 v182, v182, v110, s[4:5]
	v_cndmask_b32_e64 v182, v182, v111, s[6:7]
	v_mul_f32_e32 v182, v236, v182
	s_cmp_lt_u32 s0, 0x2b800000
	s_cbranch_scc0 .Lgdn_nomat_0_1
	v_pk_mul_f32 v[184:185], v[184:185], v[240:241] op_sel_hi:[1,0]
	v_pk_mul_f32 v[186:187], v[186:187], v[240:241] op_sel_hi:[1,0]
	v_pk_mul_f32 v[188:189], v[188:189], v[240:241] op_sel_hi:[1,0]
	v_pk_mul_f32 v[190:191], v[190:191], v[240:241] op_sel_hi:[1,0]
	v_pk_mul_f32 v[192:193], v[192:193], v[240:241] op_sel_hi:[1,0]
	v_pk_mul_f32 v[194:195], v[194:195], v[240:241] op_sel_hi:[1,0]
	v_pk_mul_f32 v[196:197], v[196:197], v[240:241] op_sel_hi:[1,0]
	v_pk_mul_f32 v[198:199], v[198:199], v[240:241] op_sel_hi:[1,0]
	v_pk_mul_f32 v[200:201], v[200:201], v[240:241] op_sel_hi:[1,0]
	v_pk_mul_f32 v[202:203], v[202:203], v[240:241] op_sel_hi:[1,0]
	v_pk_mul_f32 v[204:205], v[204:205], v[240:241] op_sel_hi:[1,0]
	v_pk_mul_f32 v[206:207], v[206:207], v[240:241] op_sel_hi:[1,0]
	v_pk_mul_f32 v[208:209], v[208:209], v[240:241] op_sel_hi:[1,0]
	v_pk_mul_f32 v[210:211], v[210:211], v[240:241] op_sel_hi:[1,0]
	v_pk_mul_f32 v[212:213], v[212:213], v[240:241] op_sel_hi:[1,0]
	v_pk_mul_f32 v[214:215], v[214:215], v[240:241] op_sel_hi:[1,0]
	v_mov_b32_e32 v240, 1.0
	v_mov_b32_e32 v89, 1.0
.Lgdn_nomat_0_1:
	v_mov_b32_e32 v238, v240
	v_mul_f32_e32 v90, v182, v89
	s_nop 1
	v_mfma_f32_16x16x4_f32 v[184:187], v62, v90, v[184:187]
	v_mfma_f32_16x16x4_f32 v[188:191], v63, v90, v[188:191]
	v_mfma_f32_16x16x4_f32 v[192:195], v64, v90, v[192:195]
	v_mfma_f32_16x16x4_f32 v[196:199], v65, v90, v[196:199]
	v_mfma_f32_16x16x4_f32 v[200:203], v66, v90, v[200:203]
	v_mfma_f32_16x16x4_f32 v[204:207], v67, v90, v[204:207]
	v_mfma_f32_16x16x4_f32 v[208:211], v68, v90, v[208:211]
	v_mfma_f32_16x16x4_f32 v[212:215], v69, v90, v[212:215]
	v_cndmask_b32_e32 v183, v82, v83, vcc
	v_cndmask_b32_e64 v183, v183, v84, s[4:5]
	v_cndmask_b32_e64 v183, v183, v85, s[6:7]
	v_mul_f32_e32 v179, v235, v183
	v_fmac_f32_e32 v179, v228, v108
	v_fmac_f32_e32 v179, v229, v109
	v_fmac_f32_e32 v179, v230, v110
	v_fmac_f32_e32 v179, v231, v111
	ds_write_b32 v172, v179 offset:1024
	s_mov_b64 exec, s[40:41]
	ds_add_u32 v91, v92 offset:0
	s_mov_b64 exec, -1
	v_add_u32_e32 v170, 0x1080, v170
	v_add_u32_e32 v237, 0x1080, v237
	v_add_u32_e32 v95, 0x1080, v95
	s_waitcnt lgkmcnt(2)
	v_mfma_f32_16x16x4_f32 v[96:99], v22, v184, 0
	v_mfma_f32_16x16x4_f32 v[100:103], v23, v185, 0
	v_mfma_f32_16x16x4_f32 v[96:99], v24, v186, v[96:99]
	v_mfma_f32_16x16x4_f32 v[100:103], v25, v187, v[100:103]
	v_mul_f32_e32 v240, v238, v139
	v_rcp_f32_e32 v89, v240
	v_readfirstlane_b32 s0, v240
	v_mfma_f32_16x16x4_f32 v[96:99], v26, v188, v[96:99]
	v_mfma_f32_16x16x4_f32 v[100:103], v27, v189, v[100:103]
	v_mfma_f32_16x16x4_f32 v[96:99], v28, v190, v[96:99]
	v_mfma_f32_16x16x4_f32 v[100:103], v29, v191, v[100:103]
	ds_read_b32 v86, v87 offset:512
	ds_read2_b32 v[62:63], v237 offset0:0 offset1:16
	ds_read2_b32 v[64:65], v237 offset0:32 offset1:48
	v_mfma_f32_16x16x4_f32 v[96:99], v30, v192, v[96:99]
	v_mfma_f32_16x16x4_f32 v[100:103], v31, v193, v[100:103]
	v_mfma_f32_16x16x4_f32 v[96:99], v32, v194, v[96:99]
	v_mfma_f32_16x16x4_f32 v[100:103], v33, v195, v[100:103]
	ds_read2_b32 v[66:67], v237 offset0:64 offset1:80
	ds_read2_b32 v[68:69], v237 offset0:96 offset1:112
	ds_read2st64_b32 v[74:75], v171 offset0:12 offset1:13
	v_mfma_f32_16x16x4_f32 v[96:99], v34, v196, v[96:99]
	v_mfma_f32_16x16x4_f32 v[100:103], v35, v197, v[100:103]
	v_mfma_f32_16x16x4_f32 v[96:99], v36, v198, v[96:99]
	v_mfma_f32_16x16x4_f32 v[100:103], v37, v199, v[100:103]
	ds_read2st64_b32 v[76:77], v171 offset0:14 offset1:15
	ds_read_b128 v[216:219], v93 offset:48
	ds_read_b128 v[220:223], v175 offset:304
	v_mfma_f32_16x16x4_f32 v[96:99], v38, v200, v[96:99]
	v_mfma_f32_16x16x4_f32 v[100:103], v39, v201, v[100:103]
	v_mfma_f32_16x16x4_f32 v[96:99], v40, v202, v[96:99]
	v_mfma_f32_16x16x4_f32 v[100:103], v41, v203, v[100:103]
	ds_read_b32 v235, v176 offset:304
	ds_read_b32 v236, v176 offset:560
	ds_read_b32 v234, v173 offset:688
	v_mfma_f32_16x16x4_f32 v[96:99], v42, v204, v[96:99]
	v_mfma_f32_16x16x4_f32 v[100:103], v43, v205, v[100:103]
	v_mfma_f32_16x16x4_f32 v[96:99], v44, v206, v[96:99]
	v_mfma_f32_16x16x4_f32 v[100:103], v45, v207, v[100:103]
	ds_read_b64 v[232:233], v173 offset:720
	ds_read_b128 v[224:227], v173 offset:752
	ds_read_b128 v[228:231], v174 offset:656
	v_mfma_f32_16x16x4_f32 v[96:99], v46, v208, v[96:99]
	v_mfma_f32_16x16x4_f32 v[100:103], v47, v209, v[100:103]
	v_mfma_f32_16x16x4_f32 v[96:99], v48, v210, v[96:99]
	v_mfma_f32_16x16x4_f32 v[100:103], v49, v211, v[100:103]
	v_mfma_f32_16x16x4_f32 v[96:99], v50, v212, v[96:99]
	v_mfma_f32_16x16x4_f32 v[100:103], v51, v213, v[100:103]
	v_mfma_f32_16x16x4_f32 v[96:99], v52, v214, v[96:99]
	v_mfma_f32_16x16x4_f32 v[100:103], v53, v215, v[100:103]
	s_nop 7
	s_nop 1
	v_pk_mul_f32 v[100:101], v[100:101], v[238:239] op_sel_hi:[1,0]
	v_pk_mul_f32 v[102:103], v[102:103], v[238:239] op_sel_hi:[1,0]
	v_pk_fma_f32 v[78:79], v[96:97], v[238:239], v[100:101] op_sel_hi:[1,0,1]
	v_pk_fma_f32 v[80:81], v[98:99], v[238:239], v[102:103] op_sel_hi:[1,0,1]
	v_pk_fma_f32 v[96:97], v[96:97], v[238:239], v[100:101] op_sel_hi:[1,0,1]
	v_pk_fma_f32 v[98:99], v[98:99], v[238:239], v[102:103] op_sel_hi:[1,0,1]
	s_nop 0
	v_permlane32_swap_b32_e32 v96, v78
	v_permlane32_swap_b32_e32 v97, v79
	v_permlane32_swap_b32_e32 v98, v80
	v_permlane32_swap_b32_e32 v99, v81
	v_mov_b32_e32 v82, v96
	v_mov_b32_e32 v83, v97
	v_mov_b32_e32 v84, v98
	v_mov_b32_e32 v85, v99
	s_nop 0
	v_permlane16_swap_b32_e32 v96, v82
	v_permlane16_swap_b32_e32 v97, v83
	v_permlane16_swap_b32_e32 v98, v84
	v_permlane16_swap_b32_e32 v99, v85
	v_fma_f32 v108, v132, v96, v70
	v_fma_f32 v109, v133, v97, v71
	v_fma_f32 v110, v134, v98, v72
	v_fma_f32 v111, v135, v99, v73
	v_fma_f32 v109, -v150, v108, v109
	v_fma_f32 v110, -v148, v108, v110
	v_fma_f32 v111, -v140, v108, v111
	v_fma_f32 v110, -v149, v109, v110
	v_fma_f32 v111, -v141, v109, v111
	v_fma_f32 v111, -v142, v110, v111
	v_cndmask_b32_e32 v182, v108, v109, vcc
	v_cndmask_b32_e64 v182, v182, v110, s[4:5]
	v_cndmask_b32_e64 v182, v182, v111, s[6:7]
	v_mul_f32_e32 v182, v152, v182
	s_cmp_lt_u32 s0, 0x2b800000
	s_cbranch_scc0 .Lgdn_nomat_1_0
	v_pk_mul_f32 v[184:185], v[184:185], v[240:241] op_sel_hi:[1,0]
	v_pk_mul_f32 v[186:187], v[186:187], v[240:241] op_sel_hi:[1,0]
	v_pk_mul_f32 v[188:189], v[188:189], v[240:241] op_sel_hi:[1,0]
	v_pk_mul_f32 v[190:191], v[190:191], v[240:241] op_sel_hi:[1,0]
	v_pk_mul_f32 v[192:193], v[192:193], v[240:241] op_sel_hi:[1,0]
	v_pk_mul_f32 v[194:195], v[194:195], v[240:241] op_sel_hi:[1,0]
	v_pk_mul_f32 v[196:197], v[196:197], v[240:241] op_sel_hi:[1,0]
	v_pk_mul_f32 v[198:199], v[198:199], v[240:241] op_sel_hi:[1,0]
	v_pk_mul_f32 v[200:201], v[200:201], v[240:241] op_sel_hi:[1,0]
	v_pk_mul_f32 v[202:203], v[202:203], v[240:241] op_sel_hi:[1,0]
	v_pk_mul_f32 v[204:205], v[204:205], v[240:241] op_sel_hi:[1,0]
	v_pk_mul_f32 v[206:207], v[206:207], v[240:241] op_sel_hi:[1,0]
	v_pk_mul_f32 v[208:209], v[208:209], v[240:241] op_sel_hi:[1,0]
	v_pk_mul_f32 v[210:211], v[210:211], v[240:241] op_sel_hi:[1,0]
	v_pk_mul_f32 v[212:213], v[212:213], v[240:241] op_sel_hi:[1,0]
	v_pk_mul_f32 v[214:215], v[214:215], v[240:241] op_sel_hi:[1,0]
	v_mov_b32_e32 v240, 1.0
	v_mov_b32_e32 v89, 1.0
.Lgdn_nomat_1_0:
	v_mov_b32_e32 v238, v240
	v_mul_f32_e32 v90, v182, v89
	s_nop 1
	v_mfma_f32_16x16x4_f32 v[184:187], v54, v90, v[184:187]
	v_mfma_f32_16x16x4_f32 v[188:191], v55, v90, v[188:191]
	v_mfma_f32_16x16x4_f32 v[192:195], v56, v90, v[192:195]
	v_mfma_f32_16x16x4_f32 v[196:199], v57, v90, v[196:199]
	v_mfma_f32_16x16x4_f32 v[200:203], v58, v90, v[200:203]
	v_mfma_f32_16x16x4_f32 v[204:207], v59, v90, v[204:207]
	v_mfma_f32_16x16x4_f32 v[208:211], v60, v90, v[208:211]
	v_mfma_f32_16x16x4_f32 v[212:215], v61, v90, v[212:215]
	v_pk_mul_f32 v[78:79], v[78:79], v[138:139] op_sel:[0,1] op_sel_hi:[1,1]
	v_pk_mul_f32 v[80:81], v[80:81], v[138:139] op_sel:[0,1] op_sel_hi:[1,1]
	v_cndmask_b32_e32 v183, v82, v83, vcc
	v_cndmask_b32_e64 v183, v183, v84, s[4:5]
	v_cndmask_b32_e64 v183, v183, v85, s[6:7]
	v_mul_f32_e32 v179, v151, v183
	v_fmac_f32_e32 v179, v144, v108
	v_fmac_f32_e32 v179, v145, v109
	v_fmac_f32_e32 v179, v146, v110
	v_fmac_f32_e32 v179, v147, v111
	ds_write_b32 v172, v179 offset:2048
	s_waitcnt lgkmcnt(1)
	v_mfma_f32_16x16x4_f32 v[96:99], v86, v182, v[78:81]
	s_nop 7
	v_mul_f32_e32 v240, v238, v223
	v_rcp_f32_e32 v89, v240
	v_readfirstlane_b32 s0, v240
	ds_read_b128 v[22:25], v169 offset:8448
	ds_read_b128 v[26:29], v169 offset:8512
	ds_read_b128 v[30:33], v169 offset:8576
	ds_read_b128 v[34:37], v169 offset:8640
	ds_read_b128 v[38:41], v169 offset:8704
	ds_read_b128 v[42:45], v169 offset:8768
	ds_read_b128 v[46:49], v169 offset:8832
	ds_read_b128 v[50:53], v169 offset:8896
	ds_read2_b32 v[54:55], v95 offset0:0 offset1:16
	ds_read2_b32 v[56:57], v95 offset0:32 offset1:48
	ds_read2_b32 v[58:59], v95 offset0:64 offset1:80
	ds_read2_b32 v[60:61], v95 offset0:96 offset1:112
	ds_read2st64_b32 v[70:71], v171 offset0:16 offset1:17
	ds_read2st64_b32 v[72:73], v171 offset0:18 offset1:19
	ds_read_b128 v[132:135], v93 offset:64
	ds_read_b128 v[136:139], v175 offset:320
	ds_read_b32 v151, v176 offset:320
	ds_read_b32 v152, v176 offset:576
	ds_read_b32 v150, v173 offset:1056
	ds_read_b64 v[148:149], v173 offset:1088
	ds_read_b128 v[140:143], v173 offset:1120
	ds_read_b128 v[144:147], v174 offset:1024
	v_mov_b32_e32 v82, v96
	v_mov_b32_e32 v83, v97
	v_mov_b32_e32 v84, v98
	v_mov_b32_e32 v85, v99
	s_nop 0
	v_permlane16_swap_b32_e32 v96, v82
	v_permlane16_swap_b32_e32 v97, v83
	v_permlane16_swap_b32_e32 v98, v84
	v_permlane16_swap_b32_e32 v99, v85
	v_fma_f32 v108, v216, v96, v74
	v_fma_f32 v109, v217, v97, v75
	v_fma_f32 v110, v218, v98, v76
	v_fma_f32 v111, v219, v99, v77
	v_fma_f32 v109, -v234, v108, v109
	v_fma_f32 v110, -v232, v108, v110
	v_fma_f32 v111, -v224, v108, v111
	v_fma_f32 v110, -v233, v109, v110
	v_fma_f32 v111, -v225, v109, v111
	v_fma_f32 v111, -v226, v110, v111
	v_cndmask_b32_e32 v182, v108, v109, vcc
	v_cndmask_b32_e64 v182, v182, v110, s[4:5]
	v_cndmask_b32_e64 v182, v182, v111, s[6:7]
	v_mul_f32_e32 v182, v236, v182
	s_cmp_lt_u32 s0, 0x2b800000
	s_cbranch_scc0 .Lgdn_nomat_1_1
	v_pk_mul_f32 v[184:185], v[184:185], v[240:241] op_sel_hi:[1,0]
	v_pk_mul_f32 v[186:187], v[186:187], v[240:241] op_sel_hi:[1,0]
	v_pk_mul_f32 v[188:189], v[188:189], v[240:241] op_sel_hi:[1,0]
	v_pk_mul_f32 v[190:191], v[190:191], v[240:241] op_sel_hi:[1,0]
	v_pk_mul_f32 v[192:193], v[192:193], v[240:241] op_sel_hi:[1,0]
	v_pk_mul_f32 v[194:195], v[194:195], v[240:241] op_sel_hi:[1,0]
	v_pk_mul_f32 v[196:197], v[196:197], v[240:241] op_sel_hi:[1,0]
	v_pk_mul_f32 v[198:199], v[198:199], v[240:241] op_sel_hi:[1,0]
	v_pk_mul_f32 v[200:201], v[200:201], v[240:241] op_sel_hi:[1,0]
	v_pk_mul_f32 v[202:203], v[202:203], v[240:241] op_sel_hi:[1,0]
	v_pk_mul_f32 v[204:205], v[204:205], v[240:241] op_sel_hi:[1,0]
	v_pk_mul_f32 v[206:207], v[206:207], v[240:241] op_sel_hi:[1,0]
	v_pk_mul_f32 v[208:209], v[208:209], v[240:241] op_sel_hi:[1,0]
	v_pk_mul_f32 v[210:211], v[210:211], v[240:241] op_sel_hi:[1,0]
	v_pk_mul_f32 v[212:213], v[212:213], v[240:241] op_sel_hi:[1,0]
	v_pk_mul_f32 v[214:215], v[214:215], v[240:241] op_sel_hi:[1,0]
	v_mov_b32_e32 v240, 1.0
	v_mov_b32_e32 v89, 1.0
.Lgdn_nomat_1_1:
	v_mov_b32_e32 v238, v240
	v_mul_f32_e32 v90, v182, v89
	s_nop 1
	v_mfma_f32_16x16x4_f32 v[184:187], v62, v90, v[184:187]
	v_mfma_f32_16x16x4_f32 v[188:191], v63, v90, v[188:191]
	v_mfma_f32_16x16x4_f32 v[192:195], v64, v90, v[192:195]
	v_mfma_f32_16x16x4_f32 v[196:199], v65, v90, v[196:199]
	v_mfma_f32_16x16x4_f32 v[200:203], v66, v90, v[200:203]
	v_mfma_f32_16x16x4_f32 v[204:207], v67, v90, v[204:207]
	v_mfma_f32_16x16x4_f32 v[208:211], v68, v90, v[208:211]
	v_mfma_f32_16x16x4_f32 v[212:215], v69, v90, v[212:215]
	v_cndmask_b32_e32 v183, v82, v83, vcc
	v_cndmask_b32_e64 v183, v183, v84, s[4:5]
	v_cndmask_b32_e64 v183, v183, v85, s[6:7]
	v_mul_f32_e32 v179, v235, v183
	v_fmac_f32_e32 v179, v228, v108
	v_fmac_f32_e32 v179, v229, v109
	v_fmac_f32_e32 v179, v230, v110
	v_fmac_f32_e32 v179, v231, v111
	ds_write_b32 v172, v179 offset:3072
	s_mov_b64 exec, s[40:41]
	ds_add_u32 v91, v92 offset:4
	s_mov_b64 exec, -1
	v_add_u32_e32 v170, 0x1080, v170
	v_add_u32_e32 v237, 0x1080, v237
	v_add_u32_e32 v95, 0x1080, v95
	s_waitcnt lgkmcnt(2)
	v_mfma_f32_16x16x4_f32 v[96:99], v22, v184, 0
	v_mfma_f32_16x16x4_f32 v[100:103], v23, v185, 0
	v_mfma_f32_16x16x4_f32 v[96:99], v24, v186, v[96:99]
	v_mfma_f32_16x16x4_f32 v[100:103], v25, v187, v[100:103]
	v_mul_f32_e32 v240, v238, v139
	v_rcp_f32_e32 v89, v240
	v_readfirstlane_b32 s0, v240
	v_mfma_f32_16x16x4_f32 v[96:99], v26, v188, v[96:99]
	v_mfma_f32_16x16x4_f32 v[100:103], v27, v189, v[100:103]
	v_mfma_f32_16x16x4_f32 v[96:99], v28, v190, v[96:99]
	v_mfma_f32_16x16x4_f32 v[100:103], v29, v191, v[100:103]
	ds_read_b32 v86, v87 offset:1024
	ds_read2_b32 v[62:63], v237 offset0:0 offset1:16
	ds_read2_b32 v[64:65], v237 offset0:32 offset1:48
	v_mfma_f32_16x16x4_f32 v[96:99], v30, v192, v[96:99]
	v_mfma_f32_16x16x4_f32 v[100:103], v31, v193, v[100:103]
	v_mfma_f32_16x16x4_f32 v[96:99], v32, v194, v[96:99]
	v_mfma_f32_16x16x4_f32 v[100:103], v33, v195, v[100:103]
	ds_read2_b32 v[66:67], v237 offset0:64 offset1:80
	ds_read2_b32 v[68:69], v237 offset0:96 offset1:112
	ds_read2st64_b32 v[74:75], v171 offset0:20 offset1:21
	v_mfma_f32_16x16x4_f32 v[96:99], v34, v196, v[96:99]
	v_mfma_f32_16x16x4_f32 v[100:103], v35, v197, v[100:103]
	v_mfma_f32_16x16x4_f32 v[96:99], v36, v198, v[96:99]
	v_mfma_f32_16x16x4_f32 v[100:103], v37, v199, v[100:103]
	ds_read2st64_b32 v[76:77], v171 offset0:22 offset1:23
	ds_read_b128 v[216:219], v93 offset:80
	ds_read_b128 v[220:223], v175 offset:336
	v_mfma_f32_16x16x4_f32 v[96:99], v38, v200, v[96:99]
	v_mfma_f32_16x16x4_f32 v[100:103], v39, v201, v[100:103]
	v_mfma_f32_16x16x4_f32 v[96:99], v40, v202, v[96:99]
	v_mfma_f32_16x16x4_f32 v[100:103], v41, v203, v[100:103]
	ds_read_b32 v235, v176 offset:336
	ds_read_b32 v236, v176 offset:592
	ds_read_b32 v234, v173 offset:1200
	v_mfma_f32_16x16x4_f32 v[96:99], v42, v204, v[96:99]
	v_mfma_f32_16x16x4_f32 v[100:103], v43, v205, v[100:103]
	v_mfma_f32_16x16x4_f32 v[96:99], v44, v206, v[96:99]
	v_mfma_f32_16x16x4_f32 v[100:103], v45, v207, v[100:103]
	ds_read_b64 v[232:233], v173 offset:1232
	ds_read_b128 v[224:227], v173 offset:1264
	ds_read_b128 v[228:231], v174 offset:1168
	v_mfma_f32_16x16x4_f32 v[96:99], v46, v208, v[96:99]
	v_mfma_f32_16x16x4_f32 v[100:103], v47, v209, v[100:103]
	v_mfma_f32_16x16x4_f32 v[96:99], v48, v210, v[96:99]
	v_mfma_f32_16x16x4_f32 v[100:103], v49, v211, v[100:103]
	v_mfma_f32_16x16x4_f32 v[96:99], v50, v212, v[96:99]
	v_mfma_f32_16x16x4_f32 v[100:103], v51, v213, v[100:103]
	v_mfma_f32_16x16x4_f32 v[96:99], v52, v214, v[96:99]
	v_mfma_f32_16x16x4_f32 v[100:103], v53, v215, v[100:103]
	s_nop 7
	s_nop 1
	v_pk_mul_f32 v[100:101], v[100:101], v[238:239] op_sel_hi:[1,0]
	v_pk_mul_f32 v[102:103], v[102:103], v[238:239] op_sel_hi:[1,0]
	v_pk_fma_f32 v[78:79], v[96:97], v[238:239], v[100:101] op_sel_hi:[1,0,1]
	v_pk_fma_f32 v[80:81], v[98:99], v[238:239], v[102:103] op_sel_hi:[1,0,1]
	v_pk_fma_f32 v[96:97], v[96:97], v[238:239], v[100:101] op_sel_hi:[1,0,1]
	v_pk_fma_f32 v[98:99], v[98:99], v[238:239], v[102:103] op_sel_hi:[1,0,1]
	s_nop 0
	v_permlane32_swap_b32_e32 v96, v78
	v_permlane32_swap_b32_e32 v97, v79
	v_permlane32_swap_b32_e32 v98, v80
	v_permlane32_swap_b32_e32 v99, v81
	v_mov_b32_e32 v82, v96
	v_mov_b32_e32 v83, v97
	v_mov_b32_e32 v84, v98
	v_mov_b32_e32 v85, v99
	s_nop 0
	v_permlane16_swap_b32_e32 v96, v82
	v_permlane16_swap_b32_e32 v97, v83
	v_permlane16_swap_b32_e32 v98, v84
	v_permlane16_swap_b32_e32 v99, v85
	v_fma_f32 v108, v132, v96, v70
	v_fma_f32 v109, v133, v97, v71
	v_fma_f32 v110, v134, v98, v72
	v_fma_f32 v111, v135, v99, v73
	v_fma_f32 v109, -v150, v108, v109
	v_fma_f32 v110, -v148, v108, v110
	v_fma_f32 v111, -v140, v108, v111
	v_fma_f32 v110, -v149, v109, v110
	v_fma_f32 v111, -v141, v109, v111
	v_fma_f32 v111, -v142, v110, v111
	v_cndmask_b32_e32 v182, v108, v109, vcc
	v_cndmask_b32_e64 v182, v182, v110, s[4:5]
	v_cndmask_b32_e64 v182, v182, v111, s[6:7]
	v_mul_f32_e32 v182, v152, v182
	s_cmp_lt_u32 s0, 0x2b800000
	s_cbranch_scc0 .Lgdn_nomat_2_0
	v_pk_mul_f32 v[184:185], v[184:185], v[240:241] op_sel_hi:[1,0]
	v_pk_mul_f32 v[186:187], v[186:187], v[240:241] op_sel_hi:[1,0]
	v_pk_mul_f32 v[188:189], v[188:189], v[240:241] op_sel_hi:[1,0]
	v_pk_mul_f32 v[190:191], v[190:191], v[240:241] op_sel_hi:[1,0]
	v_pk_mul_f32 v[192:193], v[192:193], v[240:241] op_sel_hi:[1,0]
	v_pk_mul_f32 v[194:195], v[194:195], v[240:241] op_sel_hi:[1,0]
	v_pk_mul_f32 v[196:197], v[196:197], v[240:241] op_sel_hi:[1,0]
	v_pk_mul_f32 v[198:199], v[198:199], v[240:241] op_sel_hi:[1,0]
	v_pk_mul_f32 v[200:201], v[200:201], v[240:241] op_sel_hi:[1,0]
	v_pk_mul_f32 v[202:203], v[202:203], v[240:241] op_sel_hi:[1,0]
	v_pk_mul_f32 v[204:205], v[204:205], v[240:241] op_sel_hi:[1,0]
	v_pk_mul_f32 v[206:207], v[206:207], v[240:241] op_sel_hi:[1,0]
	v_pk_mul_f32 v[208:209], v[208:209], v[240:241] op_sel_hi:[1,0]
	v_pk_mul_f32 v[210:211], v[210:211], v[240:241] op_sel_hi:[1,0]
	v_pk_mul_f32 v[212:213], v[212:213], v[240:241] op_sel_hi:[1,0]
	v_pk_mul_f32 v[214:215], v[214:215], v[240:241] op_sel_hi:[1,0]
	v_mov_b32_e32 v240, 1.0
	v_mov_b32_e32 v89, 1.0
.Lgdn_nomat_2_0:
	v_mov_b32_e32 v238, v240
	v_mul_f32_e32 v90, v182, v89
	s_nop 1
	v_mfma_f32_16x16x4_f32 v[184:187], v54, v90, v[184:187]
	v_mfma_f32_16x16x4_f32 v[188:191], v55, v90, v[188:191]
	v_mfma_f32_16x16x4_f32 v[192:195], v56, v90, v[192:195]
	v_mfma_f32_16x16x4_f32 v[196:199], v57, v90, v[196:199]
	v_mfma_f32_16x16x4_f32 v[200:203], v58, v90, v[200:203]
	v_mfma_f32_16x16x4_f32 v[204:207], v59, v90, v[204:207]
	v_mfma_f32_16x16x4_f32 v[208:211], v60, v90, v[208:211]
	v_mfma_f32_16x16x4_f32 v[212:215], v61, v90, v[212:215]
	v_pk_mul_f32 v[78:79], v[78:79], v[138:139] op_sel:[0,1] op_sel_hi:[1,1]
	v_pk_mul_f32 v[80:81], v[80:81], v[138:139] op_sel:[0,1] op_sel_hi:[1,1]
	v_cndmask_b32_e32 v183, v82, v83, vcc
	v_cndmask_b32_e64 v183, v183, v84, s[4:5]
	v_cndmask_b32_e64 v183, v183, v85, s[6:7]
	v_mul_f32_e32 v179, v151, v183
	v_fmac_f32_e32 v179, v144, v108
	v_fmac_f32_e32 v179, v145, v109
	v_fmac_f32_e32 v179, v146, v110
	v_fmac_f32_e32 v179, v147, v111
	ds_write_b32 v172, v179 offset:4096
	s_waitcnt lgkmcnt(1)
	v_mfma_f32_16x16x4_f32 v[96:99], v86, v182, v[78:81]
	s_nop 7
	v_mul_f32_e32 v240, v238, v223
	v_rcp_f32_e32 v89, v240
	v_readfirstlane_b32 s0, v240
	ds_read_b128 v[22:25], v169 offset:12672
	ds_read_b128 v[26:29], v169 offset:12736
	ds_read_b128 v[30:33], v169 offset:12800
	ds_read_b128 v[34:37], v169 offset:12864
	ds_read_b128 v[38:41], v169 offset:12928
	ds_read_b128 v[42:45], v169 offset:12992
	ds_read_b128 v[46:49], v169 offset:13056
	ds_read_b128 v[50:53], v169 offset:13120
	ds_read2_b32 v[54:55], v95 offset0:0 offset1:16
	ds_read2_b32 v[56:57], v95 offset0:32 offset1:48
	ds_read2_b32 v[58:59], v95 offset0:64 offset1:80
	ds_read2_b32 v[60:61], v95 offset0:96 offset1:112
	ds_read2st64_b32 v[70:71], v171 offset0:24 offset1:25
	ds_read2st64_b32 v[72:73], v171 offset0:26 offset1:27
	ds_read_b128 v[132:135], v93 offset:96
	ds_read_b128 v[136:139], v175 offset:352
	ds_read_b32 v151, v176 offset:352
	ds_read_b32 v152, v176 offset:608
	ds_read_b32 v150, v173 offset:1568
	ds_read_b64 v[148:149], v173 offset:1600
	ds_read_b128 v[140:143], v173 offset:1632
	ds_read_b128 v[144:147], v174 offset:1536
	v_mov_b32_e32 v82, v96
	v_mov_b32_e32 v83, v97
	v_mov_b32_e32 v84, v98
	v_mov_b32_e32 v85, v99
	s_nop 0
	v_permlane16_swap_b32_e32 v96, v82
	v_permlane16_swap_b32_e32 v97, v83
	v_permlane16_swap_b32_e32 v98, v84
	v_permlane16_swap_b32_e32 v99, v85
	v_fma_f32 v108, v216, v96, v74
	v_fma_f32 v109, v217, v97, v75
	v_fma_f32 v110, v218, v98, v76
	v_fma_f32 v111, v219, v99, v77
	v_fma_f32 v109, -v234, v108, v109
	v_fma_f32 v110, -v232, v108, v110
	v_fma_f32 v111, -v224, v108, v111
	v_fma_f32 v110, -v233, v109, v110
	v_fma_f32 v111, -v225, v109, v111
	v_fma_f32 v111, -v226, v110, v111
	v_cndmask_b32_e32 v182, v108, v109, vcc
	v_cndmask_b32_e64 v182, v182, v110, s[4:5]
	v_cndmask_b32_e64 v182, v182, v111, s[6:7]
	v_mul_f32_e32 v182, v236, v182
	s_cmp_lt_u32 s0, 0x2b800000
	s_cbranch_scc0 .Lgdn_nomat_2_1
	v_pk_mul_f32 v[184:185], v[184:185], v[240:241] op_sel_hi:[1,0]
	v_pk_mul_f32 v[186:187], v[186:187], v[240:241] op_sel_hi:[1,0]
	v_pk_mul_f32 v[188:189], v[188:189], v[240:241] op_sel_hi:[1,0]
	v_pk_mul_f32 v[190:191], v[190:191], v[240:241] op_sel_hi:[1,0]
	v_pk_mul_f32 v[192:193], v[192:193], v[240:241] op_sel_hi:[1,0]
	v_pk_mul_f32 v[194:195], v[194:195], v[240:241] op_sel_hi:[1,0]
	v_pk_mul_f32 v[196:197], v[196:197], v[240:241] op_sel_hi:[1,0]
	v_pk_mul_f32 v[198:199], v[198:199], v[240:241] op_sel_hi:[1,0]
	v_pk_mul_f32 v[200:201], v[200:201], v[240:241] op_sel_hi:[1,0]
	v_pk_mul_f32 v[202:203], v[202:203], v[240:241] op_sel_hi:[1,0]
	v_pk_mul_f32 v[204:205], v[204:205], v[240:241] op_sel_hi:[1,0]
	v_pk_mul_f32 v[206:207], v[206:207], v[240:241] op_sel_hi:[1,0]
	v_pk_mul_f32 v[208:209], v[208:209], v[240:241] op_sel_hi:[1,0]
	v_pk_mul_f32 v[210:211], v[210:211], v[240:241] op_sel_hi:[1,0]
	v_pk_mul_f32 v[212:213], v[212:213], v[240:241] op_sel_hi:[1,0]
	v_pk_mul_f32 v[214:215], v[214:215], v[240:241] op_sel_hi:[1,0]
	v_mov_b32_e32 v240, 1.0
	v_mov_b32_e32 v89, 1.0
.Lgdn_nomat_2_1:
	v_mov_b32_e32 v238, v240
	v_mul_f32_e32 v90, v182, v89
	s_nop 1
	v_mfma_f32_16x16x4_f32 v[184:187], v62, v90, v[184:187]
	v_mfma_f32_16x16x4_f32 v[188:191], v63, v90, v[188:191]
	v_mfma_f32_16x16x4_f32 v[192:195], v64, v90, v[192:195]
	v_mfma_f32_16x16x4_f32 v[196:199], v65, v90, v[196:199]
	v_mfma_f32_16x16x4_f32 v[200:203], v66, v90, v[200:203]
	v_mfma_f32_16x16x4_f32 v[204:207], v67, v90, v[204:207]
	v_mfma_f32_16x16x4_f32 v[208:211], v68, v90, v[208:211]
	v_mfma_f32_16x16x4_f32 v[212:215], v69, v90, v[212:215]
	v_cndmask_b32_e32 v183, v82, v83, vcc
	v_cndmask_b32_e64 v183, v183, v84, s[4:5]
	v_cndmask_b32_e64 v183, v183, v85, s[6:7]
	v_mul_f32_e32 v179, v235, v183
	v_fmac_f32_e32 v179, v228, v108
	v_fmac_f32_e32 v179, v229, v109
	v_fmac_f32_e32 v179, v230, v110
	v_fmac_f32_e32 v179, v231, v111
	ds_write_b32 v172, v179 offset:5120
	s_mov_b64 exec, s[40:41]
	ds_add_u32 v91, v92 offset:8
	s_mov_b64 exec, -1
	v_add_u32_e32 v170, 0x1080, v170
	v_add_u32_e32 v237, 0x1080, v237
	v_add_u32_e32 v95, 0x1080, v95
	s_waitcnt lgkmcnt(2)
	v_mfma_f32_16x16x4_f32 v[96:99], v22, v184, 0
	v_mfma_f32_16x16x4_f32 v[100:103], v23, v185, 0
	v_mfma_f32_16x16x4_f32 v[96:99], v24, v186, v[96:99]
	v_mfma_f32_16x16x4_f32 v[100:103], v25, v187, v[100:103]
	v_mul_f32_e32 v240, v238, v139
	v_rcp_f32_e32 v89, v240
	v_readfirstlane_b32 s0, v240
	v_mfma_f32_16x16x4_f32 v[96:99], v26, v188, v[96:99]
	v_mfma_f32_16x16x4_f32 v[100:103], v27, v189, v[100:103]
	v_mfma_f32_16x16x4_f32 v[96:99], v28, v190, v[96:99]
	v_mfma_f32_16x16x4_f32 v[100:103], v29, v191, v[100:103]
	ds_read_b32 v86, v87 offset:1536
	ds_read2_b32 v[62:63], v237 offset0:0 offset1:16
	ds_read2_b32 v[64:65], v237 offset0:32 offset1:48
	v_mfma_f32_16x16x4_f32 v[96:99], v30, v192, v[96:99]
	v_mfma_f32_16x16x4_f32 v[100:103], v31, v193, v[100:103]
	v_mfma_f32_16x16x4_f32 v[96:99], v32, v194, v[96:99]
	v_mfma_f32_16x16x4_f32 v[100:103], v33, v195, v[100:103]
	ds_read2_b32 v[66:67], v237 offset0:64 offset1:80
	ds_read2_b32 v[68:69], v237 offset0:96 offset1:112
	ds_read2st64_b32 v[74:75], v171 offset0:28 offset1:29
	v_mfma_f32_16x16x4_f32 v[96:99], v34, v196, v[96:99]
	v_mfma_f32_16x16x4_f32 v[100:103], v35, v197, v[100:103]
	v_mfma_f32_16x16x4_f32 v[96:99], v36, v198, v[96:99]
	v_mfma_f32_16x16x4_f32 v[100:103], v37, v199, v[100:103]
	ds_read2st64_b32 v[76:77], v171 offset0:30 offset1:31
	ds_read_b128 v[216:219], v93 offset:112
	ds_read_b128 v[220:223], v175 offset:368
	v_mfma_f32_16x16x4_f32 v[96:99], v38, v200, v[96:99]
	v_mfma_f32_16x16x4_f32 v[100:103], v39, v201, v[100:103]
	v_mfma_f32_16x16x4_f32 v[96:99], v40, v202, v[96:99]
	v_mfma_f32_16x16x4_f32 v[100:103], v41, v203, v[100:103]
	ds_read_b32 v235, v176 offset:368
	ds_read_b32 v236, v176 offset:624
	ds_read_b32 v234, v173 offset:1712
	v_mfma_f32_16x16x4_f32 v[96:99], v42, v204, v[96:99]
	v_mfma_f32_16x16x4_f32 v[100:103], v43, v205, v[100:103]
	v_mfma_f32_16x16x4_f32 v[96:99], v44, v206, v[96:99]
	v_mfma_f32_16x16x4_f32 v[100:103], v45, v207, v[100:103]
	ds_read_b64 v[232:233], v173 offset:1744
	ds_read_b128 v[224:227], v173 offset:1776
	ds_read_b128 v[228:231], v174 offset:1680
	v_mfma_f32_16x16x4_f32 v[96:99], v46, v208, v[96:99]
	v_mfma_f32_16x16x4_f32 v[100:103], v47, v209, v[100:103]
	v_mfma_f32_16x16x4_f32 v[96:99], v48, v210, v[96:99]
	v_mfma_f32_16x16x4_f32 v[100:103], v49, v211, v[100:103]
	v_mfma_f32_16x16x4_f32 v[96:99], v50, v212, v[96:99]
	v_mfma_f32_16x16x4_f32 v[100:103], v51, v213, v[100:103]
	v_mfma_f32_16x16x4_f32 v[96:99], v52, v214, v[96:99]
	v_mfma_f32_16x16x4_f32 v[100:103], v53, v215, v[100:103]
	s_nop 7
	s_nop 1
	v_pk_mul_f32 v[100:101], v[100:101], v[238:239] op_sel_hi:[1,0]
	v_pk_mul_f32 v[102:103], v[102:103], v[238:239] op_sel_hi:[1,0]
	v_pk_fma_f32 v[78:79], v[96:97], v[238:239], v[100:101] op_sel_hi:[1,0,1]
	v_pk_fma_f32 v[80:81], v[98:99], v[238:239], v[102:103] op_sel_hi:[1,0,1]
	v_pk_fma_f32 v[96:97], v[96:97], v[238:239], v[100:101] op_sel_hi:[1,0,1]
	v_pk_fma_f32 v[98:99], v[98:99], v[238:239], v[102:103] op_sel_hi:[1,0,1]
	s_nop 0
	v_permlane32_swap_b32_e32 v96, v78
	v_permlane32_swap_b32_e32 v97, v79
	v_permlane32_swap_b32_e32 v98, v80
	v_permlane32_swap_b32_e32 v99, v81
	v_mov_b32_e32 v82, v96
	v_mov_b32_e32 v83, v97
	v_mov_b32_e32 v84, v98
	v_mov_b32_e32 v85, v99
	s_nop 0
	v_permlane16_swap_b32_e32 v96, v82
	v_permlane16_swap_b32_e32 v97, v83
	v_permlane16_swap_b32_e32 v98, v84
	v_permlane16_swap_b32_e32 v99, v85
	v_fma_f32 v108, v132, v96, v70
	v_fma_f32 v109, v133, v97, v71
	v_fma_f32 v110, v134, v98, v72
	v_fma_f32 v111, v135, v99, v73
	v_fma_f32 v109, -v150, v108, v109
	v_fma_f32 v110, -v148, v108, v110
	v_fma_f32 v111, -v140, v108, v111
	v_fma_f32 v110, -v149, v109, v110
	v_fma_f32 v111, -v141, v109, v111
	v_fma_f32 v111, -v142, v110, v111
	v_cndmask_b32_e32 v182, v108, v109, vcc
	v_cndmask_b32_e64 v182, v182, v110, s[4:5]
	v_cndmask_b32_e64 v182, v182, v111, s[6:7]
	v_mul_f32_e32 v182, v152, v182
	s_cmp_lt_u32 s0, 0x2b800000
	s_cbranch_scc0 .Lgdn_nomat_3_0
	v_pk_mul_f32 v[184:185], v[184:185], v[240:241] op_sel_hi:[1,0]
	v_pk_mul_f32 v[186:187], v[186:187], v[240:241] op_sel_hi:[1,0]
	v_pk_mul_f32 v[188:189], v[188:189], v[240:241] op_sel_hi:[1,0]
	v_pk_mul_f32 v[190:191], v[190:191], v[240:241] op_sel_hi:[1,0]
	v_pk_mul_f32 v[192:193], v[192:193], v[240:241] op_sel_hi:[1,0]
	v_pk_mul_f32 v[194:195], v[194:195], v[240:241] op_sel_hi:[1,0]
	v_pk_mul_f32 v[196:197], v[196:197], v[240:241] op_sel_hi:[1,0]
	v_pk_mul_f32 v[198:199], v[198:199], v[240:241] op_sel_hi:[1,0]
	v_pk_mul_f32 v[200:201], v[200:201], v[240:241] op_sel_hi:[1,0]
	v_pk_mul_f32 v[202:203], v[202:203], v[240:241] op_sel_hi:[1,0]
	v_pk_mul_f32 v[204:205], v[204:205], v[240:241] op_sel_hi:[1,0]
	v_pk_mul_f32 v[206:207], v[206:207], v[240:241] op_sel_hi:[1,0]
	v_pk_mul_f32 v[208:209], v[208:209], v[240:241] op_sel_hi:[1,0]
	v_pk_mul_f32 v[210:211], v[210:211], v[240:241] op_sel_hi:[1,0]
	v_pk_mul_f32 v[212:213], v[212:213], v[240:241] op_sel_hi:[1,0]
	v_pk_mul_f32 v[214:215], v[214:215], v[240:241] op_sel_hi:[1,0]
	v_mov_b32_e32 v240, 1.0
	v_mov_b32_e32 v89, 1.0
.Lgdn_nomat_3_0:
	v_mov_b32_e32 v238, v240
	v_mul_f32_e32 v90, v182, v89
	s_nop 1
	v_mfma_f32_16x16x4_f32 v[184:187], v54, v90, v[184:187]
	v_mfma_f32_16x16x4_f32 v[188:191], v55, v90, v[188:191]
	v_mfma_f32_16x16x4_f32 v[192:195], v56, v90, v[192:195]
	v_mfma_f32_16x16x4_f32 v[196:199], v57, v90, v[196:199]
	v_mfma_f32_16x16x4_f32 v[200:203], v58, v90, v[200:203]
	v_mfma_f32_16x16x4_f32 v[204:207], v59, v90, v[204:207]
	v_mfma_f32_16x16x4_f32 v[208:211], v60, v90, v[208:211]
	v_mfma_f32_16x16x4_f32 v[212:215], v61, v90, v[212:215]
	v_pk_mul_f32 v[78:79], v[78:79], v[138:139] op_sel:[0,1] op_sel_hi:[1,1]
	v_pk_mul_f32 v[80:81], v[80:81], v[138:139] op_sel:[0,1] op_sel_hi:[1,1]
	v_cndmask_b32_e32 v183, v82, v83, vcc
	v_cndmask_b32_e64 v183, v183, v84, s[4:5]
	v_cndmask_b32_e64 v183, v183, v85, s[6:7]
	v_mul_f32_e32 v179, v151, v183
	v_fmac_f32_e32 v179, v144, v108
	v_fmac_f32_e32 v179, v145, v109
	v_fmac_f32_e32 v179, v146, v110
	v_fmac_f32_e32 v179, v147, v111
	ds_write_b32 v172, v179 offset:6144
	s_waitcnt lgkmcnt(1)
	v_mfma_f32_16x16x4_f32 v[96:99], v86, v182, v[78:81]
	s_nop 7
	v_mul_f32_e32 v240, v238, v223
	v_rcp_f32_e32 v89, v240
	v_readfirstlane_b32 s0, v240
	ds_read_b128 v[22:25], v169 offset:16896
	ds_read_b128 v[26:29], v169 offset:16960
	ds_read_b128 v[30:33], v169 offset:17024
	ds_read_b128 v[34:37], v169 offset:17088
	ds_read_b128 v[38:41], v169 offset:17152
	ds_read_b128 v[42:45], v169 offset:17216
	ds_read_b128 v[46:49], v169 offset:17280
	ds_read_b128 v[50:53], v169 offset:17344
	ds_read2_b32 v[54:55], v95 offset0:0 offset1:16
	ds_read2_b32 v[56:57], v95 offset0:32 offset1:48
	ds_read2_b32 v[58:59], v95 offset0:64 offset1:80
	ds_read2_b32 v[60:61], v95 offset0:96 offset1:112
	ds_read2st64_b32 v[70:71], v171 offset0:32 offset1:33
	ds_read2st64_b32 v[72:73], v171 offset0:34 offset1:35
	ds_read_b128 v[132:135], v93 offset:128
	ds_read_b128 v[136:139], v175 offset:384
	ds_read_b32 v151, v176 offset:384
	ds_read_b32 v152, v176 offset:640
	ds_read_b32 v150, v173 offset:2080
	ds_read_b64 v[148:149], v173 offset:2112
	ds_read_b128 v[140:143], v173 offset:2144
	ds_read_b128 v[144:147], v174 offset:2048
	v_mov_b32_e32 v82, v96
	v_mov_b32_e32 v83, v97
	v_mov_b32_e32 v84, v98
	v_mov_b32_e32 v85, v99
	s_nop 0
	v_permlane16_swap_b32_e32 v96, v82
	v_permlane16_swap_b32_e32 v97, v83
	v_permlane16_swap_b32_e32 v98, v84
	v_permlane16_swap_b32_e32 v99, v85
	v_fma_f32 v108, v216, v96, v74
	v_fma_f32 v109, v217, v97, v75
	v_fma_f32 v110, v218, v98, v76
	v_fma_f32 v111, v219, v99, v77
	v_fma_f32 v109, -v234, v108, v109
	v_fma_f32 v110, -v232, v108, v110
	v_fma_f32 v111, -v224, v108, v111
	v_fma_f32 v110, -v233, v109, v110
	v_fma_f32 v111, -v225, v109, v111
	v_fma_f32 v111, -v226, v110, v111
	v_cndmask_b32_e32 v182, v108, v109, vcc
	v_cndmask_b32_e64 v182, v182, v110, s[4:5]
	v_cndmask_b32_e64 v182, v182, v111, s[6:7]
	v_mul_f32_e32 v182, v236, v182
	s_cmp_lt_u32 s0, 0x2b800000
	s_cbranch_scc0 .Lgdn_nomat_3_1
	v_pk_mul_f32 v[184:185], v[184:185], v[240:241] op_sel_hi:[1,0]
	v_pk_mul_f32 v[186:187], v[186:187], v[240:241] op_sel_hi:[1,0]
	v_pk_mul_f32 v[188:189], v[188:189], v[240:241] op_sel_hi:[1,0]
	v_pk_mul_f32 v[190:191], v[190:191], v[240:241] op_sel_hi:[1,0]
	v_pk_mul_f32 v[192:193], v[192:193], v[240:241] op_sel_hi:[1,0]
	v_pk_mul_f32 v[194:195], v[194:195], v[240:241] op_sel_hi:[1,0]
	v_pk_mul_f32 v[196:197], v[196:197], v[240:241] op_sel_hi:[1,0]
	v_pk_mul_f32 v[198:199], v[198:199], v[240:241] op_sel_hi:[1,0]
	v_pk_mul_f32 v[200:201], v[200:201], v[240:241] op_sel_hi:[1,0]
	v_pk_mul_f32 v[202:203], v[202:203], v[240:241] op_sel_hi:[1,0]
	v_pk_mul_f32 v[204:205], v[204:205], v[240:241] op_sel_hi:[1,0]
	v_pk_mul_f32 v[206:207], v[206:207], v[240:241] op_sel_hi:[1,0]
	v_pk_mul_f32 v[208:209], v[208:209], v[240:241] op_sel_hi:[1,0]
	v_pk_mul_f32 v[210:211], v[210:211], v[240:241] op_sel_hi:[1,0]
	v_pk_mul_f32 v[212:213], v[212:213], v[240:241] op_sel_hi:[1,0]
	v_pk_mul_f32 v[214:215], v[214:215], v[240:241] op_sel_hi:[1,0]
	v_mov_b32_e32 v240, 1.0
	v_mov_b32_e32 v89, 1.0
.Lgdn_nomat_3_1:
	v_mov_b32_e32 v238, v240
	v_mul_f32_e32 v90, v182, v89
	s_nop 1
	v_mfma_f32_16x16x4_f32 v[184:187], v62, v90, v[184:187]
	v_mfma_f32_16x16x4_f32 v[188:191], v63, v90, v[188:191]
	v_mfma_f32_16x16x4_f32 v[192:195], v64, v90, v[192:195]
	v_mfma_f32_16x16x4_f32 v[196:199], v65, v90, v[196:199]
	v_mfma_f32_16x16x4_f32 v[200:203], v66, v90, v[200:203]
	v_mfma_f32_16x16x4_f32 v[204:207], v67, v90, v[204:207]
	v_mfma_f32_16x16x4_f32 v[208:211], v68, v90, v[208:211]
	v_mfma_f32_16x16x4_f32 v[212:215], v69, v90, v[212:215]
	v_cndmask_b32_e32 v183, v82, v83, vcc
	v_cndmask_b32_e64 v183, v183, v84, s[4:5]
	v_cndmask_b32_e64 v183, v183, v85, s[6:7]
	v_mul_f32_e32 v179, v235, v183
	v_fmac_f32_e32 v179, v228, v108
	v_fmac_f32_e32 v179, v229, v109
	v_fmac_f32_e32 v179, v230, v110
	v_fmac_f32_e32 v179, v231, v111
	ds_write_b32 v172, v179 offset:7168
	s_mov_b64 exec, s[40:41]
	ds_add_u32 v91, v92 offset:12
	s_mov_b64 exec, -1
	v_add_u32_e32 v170, 0x1080, v170
	v_add_u32_e32 v237, 0x1080, v237
	v_add_u32_e32 v95, 0x1080, v95
	s_waitcnt lgkmcnt(2)
	v_mfma_f32_16x16x4_f32 v[96:99], v22, v184, 0
	v_mfma_f32_16x16x4_f32 v[100:103], v23, v185, 0
	v_mfma_f32_16x16x4_f32 v[96:99], v24, v186, v[96:99]
	v_mfma_f32_16x16x4_f32 v[100:103], v25, v187, v[100:103]
	v_mul_f32_e32 v240, v238, v139
	v_rcp_f32_e32 v89, v240
	v_readfirstlane_b32 s0, v240
	v_mfma_f32_16x16x4_f32 v[96:99], v26, v188, v[96:99]
	v_mfma_f32_16x16x4_f32 v[100:103], v27, v189, v[100:103]
	v_mfma_f32_16x16x4_f32 v[96:99], v28, v190, v[96:99]
	v_mfma_f32_16x16x4_f32 v[100:103], v29, v191, v[100:103]
	ds_read_b32 v86, v87 offset:2048
	ds_read2_b32 v[62:63], v237 offset0:0 offset1:16
	ds_read2_b32 v[64:65], v237 offset0:32 offset1:48
	v_mfma_f32_16x16x4_f32 v[96:99], v30, v192, v[96:99]
	v_mfma_f32_16x16x4_f32 v[100:103], v31, v193, v[100:103]
	v_mfma_f32_16x16x4_f32 v[96:99], v32, v194, v[96:99]
	v_mfma_f32_16x16x4_f32 v[100:103], v33, v195, v[100:103]
	ds_read2_b32 v[66:67], v237 offset0:64 offset1:80
	ds_read2_b32 v[68:69], v237 offset0:96 offset1:112
	ds_read2st64_b32 v[74:75], v171 offset0:36 offset1:37
	v_mfma_f32_16x16x4_f32 v[96:99], v34, v196, v[96:99]
	v_mfma_f32_16x16x4_f32 v[100:103], v35, v197, v[100:103]
	v_mfma_f32_16x16x4_f32 v[96:99], v36, v198, v[96:99]
	v_mfma_f32_16x16x4_f32 v[100:103], v37, v199, v[100:103]
	ds_read2st64_b32 v[76:77], v171 offset0:38 offset1:39
	ds_read_b128 v[216:219], v93 offset:144
	ds_read_b128 v[220:223], v175 offset:400
	v_mfma_f32_16x16x4_f32 v[96:99], v38, v200, v[96:99]
	v_mfma_f32_16x16x4_f32 v[100:103], v39, v201, v[100:103]
	v_mfma_f32_16x16x4_f32 v[96:99], v40, v202, v[96:99]
	v_mfma_f32_16x16x4_f32 v[100:103], v41, v203, v[100:103]
	ds_read_b32 v235, v176 offset:400
	ds_read_b32 v236, v176 offset:656
	ds_read_b32 v234, v173 offset:2224
	v_mfma_f32_16x16x4_f32 v[96:99], v42, v204, v[96:99]
	v_mfma_f32_16x16x4_f32 v[100:103], v43, v205, v[100:103]
	v_mfma_f32_16x16x4_f32 v[96:99], v44, v206, v[96:99]
	v_mfma_f32_16x16x4_f32 v[100:103], v45, v207, v[100:103]
	ds_read_b64 v[232:233], v173 offset:2256
	ds_read_b128 v[224:227], v173 offset:2288
	ds_read_b128 v[228:231], v174 offset:2192
	v_mfma_f32_16x16x4_f32 v[96:99], v46, v208, v[96:99]
	v_mfma_f32_16x16x4_f32 v[100:103], v47, v209, v[100:103]
	v_mfma_f32_16x16x4_f32 v[96:99], v48, v210, v[96:99]
	v_mfma_f32_16x16x4_f32 v[100:103], v49, v211, v[100:103]
	v_mfma_f32_16x16x4_f32 v[96:99], v50, v212, v[96:99]
	v_mfma_f32_16x16x4_f32 v[100:103], v51, v213, v[100:103]
	v_mfma_f32_16x16x4_f32 v[96:99], v52, v214, v[96:99]
	v_mfma_f32_16x16x4_f32 v[100:103], v53, v215, v[100:103]
	s_nop 7
	s_nop 1
	v_pk_mul_f32 v[100:101], v[100:101], v[238:239] op_sel_hi:[1,0]
	v_pk_mul_f32 v[102:103], v[102:103], v[238:239] op_sel_hi:[1,0]
	v_pk_fma_f32 v[78:79], v[96:97], v[238:239], v[100:101] op_sel_hi:[1,0,1]
	v_pk_fma_f32 v[80:81], v[98:99], v[238:239], v[102:103] op_sel_hi:[1,0,1]
	v_pk_fma_f32 v[96:97], v[96:97], v[238:239], v[100:101] op_sel_hi:[1,0,1]
	v_pk_fma_f32 v[98:99], v[98:99], v[238:239], v[102:103] op_sel_hi:[1,0,1]
	s_nop 0
	v_permlane32_swap_b32_e32 v96, v78
	v_permlane32_swap_b32_e32 v97, v79
	v_permlane32_swap_b32_e32 v98, v80
	v_permlane32_swap_b32_e32 v99, v81
	v_mov_b32_e32 v82, v96
	v_mov_b32_e32 v83, v97
	v_mov_b32_e32 v84, v98
	v_mov_b32_e32 v85, v99
	s_nop 0
	v_permlane16_swap_b32_e32 v96, v82
	v_permlane16_swap_b32_e32 v97, v83
	v_permlane16_swap_b32_e32 v98, v84
	v_permlane16_swap_b32_e32 v99, v85
	v_fma_f32 v108, v132, v96, v70
	v_fma_f32 v109, v133, v97, v71
	v_fma_f32 v110, v134, v98, v72
	v_fma_f32 v111, v135, v99, v73
	v_fma_f32 v109, -v150, v108, v109
	v_fma_f32 v110, -v148, v108, v110
	v_fma_f32 v111, -v140, v108, v111
	v_fma_f32 v110, -v149, v109, v110
	v_fma_f32 v111, -v141, v109, v111
	v_fma_f32 v111, -v142, v110, v111
	v_cndmask_b32_e32 v182, v108, v109, vcc
	v_cndmask_b32_e64 v182, v182, v110, s[4:5]
	v_cndmask_b32_e64 v182, v182, v111, s[6:7]
	v_mul_f32_e32 v182, v152, v182
	s_cmp_lt_u32 s0, 0x2b800000
	s_cbranch_scc0 .Lgdn_nomat_4_0
	v_pk_mul_f32 v[184:185], v[184:185], v[240:241] op_sel_hi:[1,0]
	v_pk_mul_f32 v[186:187], v[186:187], v[240:241] op_sel_hi:[1,0]
	v_pk_mul_f32 v[188:189], v[188:189], v[240:241] op_sel_hi:[1,0]
	v_pk_mul_f32 v[190:191], v[190:191], v[240:241] op_sel_hi:[1,0]
	v_pk_mul_f32 v[192:193], v[192:193], v[240:241] op_sel_hi:[1,0]
	v_pk_mul_f32 v[194:195], v[194:195], v[240:241] op_sel_hi:[1,0]
	v_pk_mul_f32 v[196:197], v[196:197], v[240:241] op_sel_hi:[1,0]
	v_pk_mul_f32 v[198:199], v[198:199], v[240:241] op_sel_hi:[1,0]
	v_pk_mul_f32 v[200:201], v[200:201], v[240:241] op_sel_hi:[1,0]
	v_pk_mul_f32 v[202:203], v[202:203], v[240:241] op_sel_hi:[1,0]
	v_pk_mul_f32 v[204:205], v[204:205], v[240:241] op_sel_hi:[1,0]
	v_pk_mul_f32 v[206:207], v[206:207], v[240:241] op_sel_hi:[1,0]
	v_pk_mul_f32 v[208:209], v[208:209], v[240:241] op_sel_hi:[1,0]
	v_pk_mul_f32 v[210:211], v[210:211], v[240:241] op_sel_hi:[1,0]
	v_pk_mul_f32 v[212:213], v[212:213], v[240:241] op_sel_hi:[1,0]
	v_pk_mul_f32 v[214:215], v[214:215], v[240:241] op_sel_hi:[1,0]
	v_mov_b32_e32 v240, 1.0
	v_mov_b32_e32 v89, 1.0
.Lgdn_nomat_4_0:
	v_mov_b32_e32 v238, v240
	v_mul_f32_e32 v90, v182, v89
	s_nop 1
	v_mfma_f32_16x16x4_f32 v[184:187], v54, v90, v[184:187]
	v_mfma_f32_16x16x4_f32 v[188:191], v55, v90, v[188:191]
	v_mfma_f32_16x16x4_f32 v[192:195], v56, v90, v[192:195]
	v_mfma_f32_16x16x4_f32 v[196:199], v57, v90, v[196:199]
	v_mfma_f32_16x16x4_f32 v[200:203], v58, v90, v[200:203]
	v_mfma_f32_16x16x4_f32 v[204:207], v59, v90, v[204:207]
	v_mfma_f32_16x16x4_f32 v[208:211], v60, v90, v[208:211]
	v_mfma_f32_16x16x4_f32 v[212:215], v61, v90, v[212:215]
	v_pk_mul_f32 v[78:79], v[78:79], v[138:139] op_sel:[0,1] op_sel_hi:[1,1]
	v_pk_mul_f32 v[80:81], v[80:81], v[138:139] op_sel:[0,1] op_sel_hi:[1,1]
	v_cndmask_b32_e32 v183, v82, v83, vcc
	v_cndmask_b32_e64 v183, v183, v84, s[4:5]
	v_cndmask_b32_e64 v183, v183, v85, s[6:7]
	v_mul_f32_e32 v179, v151, v183
	v_fmac_f32_e32 v179, v144, v108
	v_fmac_f32_e32 v179, v145, v109
	v_fmac_f32_e32 v179, v146, v110
	v_fmac_f32_e32 v179, v147, v111
	ds_write_b32 v172, v179 offset:8192
	s_waitcnt lgkmcnt(1)
	v_mfma_f32_16x16x4_f32 v[96:99], v86, v182, v[78:81]
	s_nop 7
	v_mul_f32_e32 v240, v238, v223
	v_rcp_f32_e32 v89, v240
	v_readfirstlane_b32 s0, v240
	ds_read_b128 v[22:25], v169 offset:21120
	ds_read_b128 v[26:29], v169 offset:21184
	ds_read_b128 v[30:33], v169 offset:21248
	ds_read_b128 v[34:37], v169 offset:21312
	ds_read_b128 v[38:41], v169 offset:21376
	ds_read_b128 v[42:45], v169 offset:21440
	ds_read_b128 v[46:49], v169 offset:21504
	ds_read_b128 v[50:53], v169 offset:21568
	ds_read2_b32 v[54:55], v95 offset0:0 offset1:16
	ds_read2_b32 v[56:57], v95 offset0:32 offset1:48
	ds_read2_b32 v[58:59], v95 offset0:64 offset1:80
	ds_read2_b32 v[60:61], v95 offset0:96 offset1:112
	ds_read2st64_b32 v[70:71], v171 offset0:40 offset1:41
	ds_read2st64_b32 v[72:73], v171 offset0:42 offset1:43
	ds_read_b128 v[132:135], v93 offset:160
	ds_read_b128 v[136:139], v175 offset:416
	ds_read_b32 v151, v176 offset:416
	ds_read_b32 v152, v176 offset:672
	ds_read_b32 v150, v173 offset:2592
	ds_read_b64 v[148:149], v173 offset:2624
	ds_read_b128 v[140:143], v173 offset:2656
	ds_read_b128 v[144:147], v174 offset:2560
	v_mov_b32_e32 v82, v96
	v_mov_b32_e32 v83, v97
	v_mov_b32_e32 v84, v98
	v_mov_b32_e32 v85, v99
	s_nop 0
	v_permlane16_swap_b32_e32 v96, v82
	v_permlane16_swap_b32_e32 v97, v83
	v_permlane16_swap_b32_e32 v98, v84
	v_permlane16_swap_b32_e32 v99, v85
	v_fma_f32 v108, v216, v96, v74
	v_fma_f32 v109, v217, v97, v75
	v_fma_f32 v110, v218, v98, v76
	v_fma_f32 v111, v219, v99, v77
	v_fma_f32 v109, -v234, v108, v109
	v_fma_f32 v110, -v232, v108, v110
	v_fma_f32 v111, -v224, v108, v111
	v_fma_f32 v110, -v233, v109, v110
	v_fma_f32 v111, -v225, v109, v111
	v_fma_f32 v111, -v226, v110, v111
	v_cndmask_b32_e32 v182, v108, v109, vcc
	v_cndmask_b32_e64 v182, v182, v110, s[4:5]
	v_cndmask_b32_e64 v182, v182, v111, s[6:7]
	v_mul_f32_e32 v182, v236, v182
	s_cmp_lt_u32 s0, 0x2b800000
	s_cbranch_scc0 .Lgdn_nomat_4_1
	v_pk_mul_f32 v[184:185], v[184:185], v[240:241] op_sel_hi:[1,0]
	v_pk_mul_f32 v[186:187], v[186:187], v[240:241] op_sel_hi:[1,0]
	v_pk_mul_f32 v[188:189], v[188:189], v[240:241] op_sel_hi:[1,0]
	v_pk_mul_f32 v[190:191], v[190:191], v[240:241] op_sel_hi:[1,0]
	v_pk_mul_f32 v[192:193], v[192:193], v[240:241] op_sel_hi:[1,0]
	v_pk_mul_f32 v[194:195], v[194:195], v[240:241] op_sel_hi:[1,0]
	v_pk_mul_f32 v[196:197], v[196:197], v[240:241] op_sel_hi:[1,0]
	v_pk_mul_f32 v[198:199], v[198:199], v[240:241] op_sel_hi:[1,0]
	v_pk_mul_f32 v[200:201], v[200:201], v[240:241] op_sel_hi:[1,0]
	v_pk_mul_f32 v[202:203], v[202:203], v[240:241] op_sel_hi:[1,0]
	v_pk_mul_f32 v[204:205], v[204:205], v[240:241] op_sel_hi:[1,0]
	v_pk_mul_f32 v[206:207], v[206:207], v[240:241] op_sel_hi:[1,0]
	v_pk_mul_f32 v[208:209], v[208:209], v[240:241] op_sel_hi:[1,0]
	v_pk_mul_f32 v[210:211], v[210:211], v[240:241] op_sel_hi:[1,0]
	v_pk_mul_f32 v[212:213], v[212:213], v[240:241] op_sel_hi:[1,0]
	v_pk_mul_f32 v[214:215], v[214:215], v[240:241] op_sel_hi:[1,0]
	v_mov_b32_e32 v240, 1.0
	v_mov_b32_e32 v89, 1.0
.Lgdn_nomat_4_1:
	v_mov_b32_e32 v238, v240
	v_mul_f32_e32 v90, v182, v89
	s_nop 1
	v_mfma_f32_16x16x4_f32 v[184:187], v62, v90, v[184:187]
	v_mfma_f32_16x16x4_f32 v[188:191], v63, v90, v[188:191]
	v_mfma_f32_16x16x4_f32 v[192:195], v64, v90, v[192:195]
	v_mfma_f32_16x16x4_f32 v[196:199], v65, v90, v[196:199]
	v_mfma_f32_16x16x4_f32 v[200:203], v66, v90, v[200:203]
	v_mfma_f32_16x16x4_f32 v[204:207], v67, v90, v[204:207]
	v_mfma_f32_16x16x4_f32 v[208:211], v68, v90, v[208:211]
	v_mfma_f32_16x16x4_f32 v[212:215], v69, v90, v[212:215]
	v_cndmask_b32_e32 v183, v82, v83, vcc
	v_cndmask_b32_e64 v183, v183, v84, s[4:5]
	v_cndmask_b32_e64 v183, v183, v85, s[6:7]
	v_mul_f32_e32 v179, v235, v183
	v_fmac_f32_e32 v179, v228, v108
	v_fmac_f32_e32 v179, v229, v109
	v_fmac_f32_e32 v179, v230, v110
	v_fmac_f32_e32 v179, v231, v111
	ds_write_b32 v172, v179 offset:9216
	s_mov_b64 exec, s[40:41]
	ds_add_u32 v91, v92 offset:16
	s_mov_b64 exec, -1
	v_add_u32_e32 v170, 0x1080, v170
	v_add_u32_e32 v237, 0x1080, v237
	v_add_u32_e32 v95, 0x1080, v95
	s_waitcnt lgkmcnt(2)
	v_mfma_f32_16x16x4_f32 v[96:99], v22, v184, 0
	v_mfma_f32_16x16x4_f32 v[100:103], v23, v185, 0
	v_mfma_f32_16x16x4_f32 v[96:99], v24, v186, v[96:99]
	v_mfma_f32_16x16x4_f32 v[100:103], v25, v187, v[100:103]
	v_mul_f32_e32 v240, v238, v139
	v_rcp_f32_e32 v89, v240
	v_readfirstlane_b32 s0, v240
	v_mfma_f32_16x16x4_f32 v[96:99], v26, v188, v[96:99]
	v_mfma_f32_16x16x4_f32 v[100:103], v27, v189, v[100:103]
	v_mfma_f32_16x16x4_f32 v[96:99], v28, v190, v[96:99]
	v_mfma_f32_16x16x4_f32 v[100:103], v29, v191, v[100:103]
	ds_read_b32 v86, v87 offset:2560
	ds_read2_b32 v[62:63], v237 offset0:0 offset1:16
	ds_read2_b32 v[64:65], v237 offset0:32 offset1:48
	v_mfma_f32_16x16x4_f32 v[96:99], v30, v192, v[96:99]
	v_mfma_f32_16x16x4_f32 v[100:103], v31, v193, v[100:103]
	v_mfma_f32_16x16x4_f32 v[96:99], v32, v194, v[96:99]
	v_mfma_f32_16x16x4_f32 v[100:103], v33, v195, v[100:103]
	ds_read2_b32 v[66:67], v237 offset0:64 offset1:80
	ds_read2_b32 v[68:69], v237 offset0:96 offset1:112
	ds_read2st64_b32 v[74:75], v171 offset0:44 offset1:45
	v_mfma_f32_16x16x4_f32 v[96:99], v34, v196, v[96:99]
	v_mfma_f32_16x16x4_f32 v[100:103], v35, v197, v[100:103]
	v_mfma_f32_16x16x4_f32 v[96:99], v36, v198, v[96:99]
	v_mfma_f32_16x16x4_f32 v[100:103], v37, v199, v[100:103]
	ds_read2st64_b32 v[76:77], v171 offset0:46 offset1:47
	ds_read_b128 v[216:219], v93 offset:176
	ds_read_b128 v[220:223], v175 offset:432
	v_mfma_f32_16x16x4_f32 v[96:99], v38, v200, v[96:99]
	v_mfma_f32_16x16x4_f32 v[100:103], v39, v201, v[100:103]
	v_mfma_f32_16x16x4_f32 v[96:99], v40, v202, v[96:99]
	v_mfma_f32_16x16x4_f32 v[100:103], v41, v203, v[100:103]
	ds_read_b32 v235, v176 offset:432
	ds_read_b32 v236, v176 offset:688
	ds_read_b32 v234, v173 offset:2736
	v_mfma_f32_16x16x4_f32 v[96:99], v42, v204, v[96:99]
	v_mfma_f32_16x16x4_f32 v[100:103], v43, v205, v[100:103]
	v_mfma_f32_16x16x4_f32 v[96:99], v44, v206, v[96:99]
	v_mfma_f32_16x16x4_f32 v[100:103], v45, v207, v[100:103]
	ds_read_b64 v[232:233], v173 offset:2768
	ds_read_b128 v[224:227], v173 offset:2800
	ds_read_b128 v[228:231], v174 offset:2704
	v_mfma_f32_16x16x4_f32 v[96:99], v46, v208, v[96:99]
	v_mfma_f32_16x16x4_f32 v[100:103], v47, v209, v[100:103]
	v_mfma_f32_16x16x4_f32 v[96:99], v48, v210, v[96:99]
	v_mfma_f32_16x16x4_f32 v[100:103], v49, v211, v[100:103]
	v_mfma_f32_16x16x4_f32 v[96:99], v50, v212, v[96:99]
	v_mfma_f32_16x16x4_f32 v[100:103], v51, v213, v[100:103]
	v_mfma_f32_16x16x4_f32 v[96:99], v52, v214, v[96:99]
	v_mfma_f32_16x16x4_f32 v[100:103], v53, v215, v[100:103]
	s_nop 7
	s_nop 1
	v_pk_mul_f32 v[100:101], v[100:101], v[238:239] op_sel_hi:[1,0]
	v_pk_mul_f32 v[102:103], v[102:103], v[238:239] op_sel_hi:[1,0]
	v_pk_fma_f32 v[78:79], v[96:97], v[238:239], v[100:101] op_sel_hi:[1,0,1]
	v_pk_fma_f32 v[80:81], v[98:99], v[238:239], v[102:103] op_sel_hi:[1,0,1]
	v_pk_fma_f32 v[96:97], v[96:97], v[238:239], v[100:101] op_sel_hi:[1,0,1]
	v_pk_fma_f32 v[98:99], v[98:99], v[238:239], v[102:103] op_sel_hi:[1,0,1]
	s_nop 0
	v_permlane32_swap_b32_e32 v96, v78
	v_permlane32_swap_b32_e32 v97, v79
	v_permlane32_swap_b32_e32 v98, v80
	v_permlane32_swap_b32_e32 v99, v81
	v_mov_b32_e32 v82, v96
	v_mov_b32_e32 v83, v97
	v_mov_b32_e32 v84, v98
	v_mov_b32_e32 v85, v99
	s_nop 0
	v_permlane16_swap_b32_e32 v96, v82
	v_permlane16_swap_b32_e32 v97, v83
	v_permlane16_swap_b32_e32 v98, v84
	v_permlane16_swap_b32_e32 v99, v85
	v_fma_f32 v108, v132, v96, v70
	v_fma_f32 v109, v133, v97, v71
	v_fma_f32 v110, v134, v98, v72
	v_fma_f32 v111, v135, v99, v73
	v_fma_f32 v109, -v150, v108, v109
	v_fma_f32 v110, -v148, v108, v110
	v_fma_f32 v111, -v140, v108, v111
	v_fma_f32 v110, -v149, v109, v110
	v_fma_f32 v111, -v141, v109, v111
	v_fma_f32 v111, -v142, v110, v111
	v_cndmask_b32_e32 v182, v108, v109, vcc
	v_cndmask_b32_e64 v182, v182, v110, s[4:5]
	v_cndmask_b32_e64 v182, v182, v111, s[6:7]
	v_mul_f32_e32 v182, v152, v182
	s_cmp_lt_u32 s0, 0x2b800000
	s_cbranch_scc0 .Lgdn_nomat_5_0
	v_pk_mul_f32 v[184:185], v[184:185], v[240:241] op_sel_hi:[1,0]
	v_pk_mul_f32 v[186:187], v[186:187], v[240:241] op_sel_hi:[1,0]
	v_pk_mul_f32 v[188:189], v[188:189], v[240:241] op_sel_hi:[1,0]
	v_pk_mul_f32 v[190:191], v[190:191], v[240:241] op_sel_hi:[1,0]
	v_pk_mul_f32 v[192:193], v[192:193], v[240:241] op_sel_hi:[1,0]
	v_pk_mul_f32 v[194:195], v[194:195], v[240:241] op_sel_hi:[1,0]
	v_pk_mul_f32 v[196:197], v[196:197], v[240:241] op_sel_hi:[1,0]
	v_pk_mul_f32 v[198:199], v[198:199], v[240:241] op_sel_hi:[1,0]
	v_pk_mul_f32 v[200:201], v[200:201], v[240:241] op_sel_hi:[1,0]
	v_pk_mul_f32 v[202:203], v[202:203], v[240:241] op_sel_hi:[1,0]
	v_pk_mul_f32 v[204:205], v[204:205], v[240:241] op_sel_hi:[1,0]
	v_pk_mul_f32 v[206:207], v[206:207], v[240:241] op_sel_hi:[1,0]
	v_pk_mul_f32 v[208:209], v[208:209], v[240:241] op_sel_hi:[1,0]
	v_pk_mul_f32 v[210:211], v[210:211], v[240:241] op_sel_hi:[1,0]
	v_pk_mul_f32 v[212:213], v[212:213], v[240:241] op_sel_hi:[1,0]
	v_pk_mul_f32 v[214:215], v[214:215], v[240:241] op_sel_hi:[1,0]
	v_mov_b32_e32 v240, 1.0
	v_mov_b32_e32 v89, 1.0
.Lgdn_nomat_5_0:
	v_mov_b32_e32 v238, v240
	v_mul_f32_e32 v90, v182, v89
	s_nop 1
	v_mfma_f32_16x16x4_f32 v[184:187], v54, v90, v[184:187]
	v_mfma_f32_16x16x4_f32 v[188:191], v55, v90, v[188:191]
	v_mfma_f32_16x16x4_f32 v[192:195], v56, v90, v[192:195]
	v_mfma_f32_16x16x4_f32 v[196:199], v57, v90, v[196:199]
	v_mfma_f32_16x16x4_f32 v[200:203], v58, v90, v[200:203]
	v_mfma_f32_16x16x4_f32 v[204:207], v59, v90, v[204:207]
	v_mfma_f32_16x16x4_f32 v[208:211], v60, v90, v[208:211]
	v_mfma_f32_16x16x4_f32 v[212:215], v61, v90, v[212:215]
	v_pk_mul_f32 v[78:79], v[78:79], v[138:139] op_sel:[0,1] op_sel_hi:[1,1]
	v_pk_mul_f32 v[80:81], v[80:81], v[138:139] op_sel:[0,1] op_sel_hi:[1,1]
	v_cndmask_b32_e32 v183, v82, v83, vcc
	v_cndmask_b32_e64 v183, v183, v84, s[4:5]
	v_cndmask_b32_e64 v183, v183, v85, s[6:7]
	v_mul_f32_e32 v179, v151, v183
	v_fmac_f32_e32 v179, v144, v108
	v_fmac_f32_e32 v179, v145, v109
	v_fmac_f32_e32 v179, v146, v110
	v_fmac_f32_e32 v179, v147, v111
	ds_write_b32 v172, v179 offset:10240
	s_waitcnt lgkmcnt(1)
	v_mfma_f32_16x16x4_f32 v[96:99], v86, v182, v[78:81]
	s_nop 7
	v_mul_f32_e32 v240, v238, v223
	v_rcp_f32_e32 v89, v240
	v_readfirstlane_b32 s0, v240
	ds_read_b128 v[22:25], v169 offset:25344
	ds_read_b128 v[26:29], v169 offset:25408
	ds_read_b128 v[30:33], v169 offset:25472
	ds_read_b128 v[34:37], v169 offset:25536
	ds_read_b128 v[38:41], v169 offset:25600
	ds_read_b128 v[42:45], v169 offset:25664
	ds_read_b128 v[46:49], v169 offset:25728
	ds_read_b128 v[50:53], v169 offset:25792
	ds_read2_b32 v[54:55], v95 offset0:0 offset1:16
	ds_read2_b32 v[56:57], v95 offset0:32 offset1:48
	ds_read2_b32 v[58:59], v95 offset0:64 offset1:80
	ds_read2_b32 v[60:61], v95 offset0:96 offset1:112
	ds_read2st64_b32 v[70:71], v171 offset0:48 offset1:49
	ds_read2st64_b32 v[72:73], v171 offset0:50 offset1:51
	ds_read_b128 v[132:135], v93 offset:192
	ds_read_b128 v[136:139], v175 offset:448
	ds_read_b32 v151, v176 offset:448
	ds_read_b32 v152, v176 offset:704
	ds_read_b32 v150, v173 offset:3104
	ds_read_b64 v[148:149], v173 offset:3136
	ds_read_b128 v[140:143], v173 offset:3168
	ds_read_b128 v[144:147], v174 offset:3072
	v_mov_b32_e32 v82, v96
	v_mov_b32_e32 v83, v97
	v_mov_b32_e32 v84, v98
	v_mov_b32_e32 v85, v99
	s_nop 0
	v_permlane16_swap_b32_e32 v96, v82
	v_permlane16_swap_b32_e32 v97, v83
	v_permlane16_swap_b32_e32 v98, v84
	v_permlane16_swap_b32_e32 v99, v85
	v_fma_f32 v108, v216, v96, v74
	v_fma_f32 v109, v217, v97, v75
	v_fma_f32 v110, v218, v98, v76
	v_fma_f32 v111, v219, v99, v77
	v_fma_f32 v109, -v234, v108, v109
	v_fma_f32 v110, -v232, v108, v110
	v_fma_f32 v111, -v224, v108, v111
	v_fma_f32 v110, -v233, v109, v110
	v_fma_f32 v111, -v225, v109, v111
	v_fma_f32 v111, -v226, v110, v111
	v_cndmask_b32_e32 v182, v108, v109, vcc
	v_cndmask_b32_e64 v182, v182, v110, s[4:5]
	v_cndmask_b32_e64 v182, v182, v111, s[6:7]
	v_mul_f32_e32 v182, v236, v182
	s_cmp_lt_u32 s0, 0x2b800000
	s_cbranch_scc0 .Lgdn_nomat_5_1
	v_pk_mul_f32 v[184:185], v[184:185], v[240:241] op_sel_hi:[1,0]
	v_pk_mul_f32 v[186:187], v[186:187], v[240:241] op_sel_hi:[1,0]
	v_pk_mul_f32 v[188:189], v[188:189], v[240:241] op_sel_hi:[1,0]
	v_pk_mul_f32 v[190:191], v[190:191], v[240:241] op_sel_hi:[1,0]
	v_pk_mul_f32 v[192:193], v[192:193], v[240:241] op_sel_hi:[1,0]
	v_pk_mul_f32 v[194:195], v[194:195], v[240:241] op_sel_hi:[1,0]
	v_pk_mul_f32 v[196:197], v[196:197], v[240:241] op_sel_hi:[1,0]
	v_pk_mul_f32 v[198:199], v[198:199], v[240:241] op_sel_hi:[1,0]
	v_pk_mul_f32 v[200:201], v[200:201], v[240:241] op_sel_hi:[1,0]
	v_pk_mul_f32 v[202:203], v[202:203], v[240:241] op_sel_hi:[1,0]
	v_pk_mul_f32 v[204:205], v[204:205], v[240:241] op_sel_hi:[1,0]
	v_pk_mul_f32 v[206:207], v[206:207], v[240:241] op_sel_hi:[1,0]
	v_pk_mul_f32 v[208:209], v[208:209], v[240:241] op_sel_hi:[1,0]
	v_pk_mul_f32 v[210:211], v[210:211], v[240:241] op_sel_hi:[1,0]
	v_pk_mul_f32 v[212:213], v[212:213], v[240:241] op_sel_hi:[1,0]
	v_pk_mul_f32 v[214:215], v[214:215], v[240:241] op_sel_hi:[1,0]
	v_mov_b32_e32 v240, 1.0
	v_mov_b32_e32 v89, 1.0
.Lgdn_nomat_5_1:
	v_mov_b32_e32 v238, v240
	v_mul_f32_e32 v90, v182, v89
	s_nop 1
	v_mfma_f32_16x16x4_f32 v[184:187], v62, v90, v[184:187]
	v_mfma_f32_16x16x4_f32 v[188:191], v63, v90, v[188:191]
	v_mfma_f32_16x16x4_f32 v[192:195], v64, v90, v[192:195]
	v_mfma_f32_16x16x4_f32 v[196:199], v65, v90, v[196:199]
	v_mfma_f32_16x16x4_f32 v[200:203], v66, v90, v[200:203]
	v_mfma_f32_16x16x4_f32 v[204:207], v67, v90, v[204:207]
	v_mfma_f32_16x16x4_f32 v[208:211], v68, v90, v[208:211]
	v_mfma_f32_16x16x4_f32 v[212:215], v69, v90, v[212:215]
	v_cndmask_b32_e32 v183, v82, v83, vcc
	v_cndmask_b32_e64 v183, v183, v84, s[4:5]
	v_cndmask_b32_e64 v183, v183, v85, s[6:7]
	v_mul_f32_e32 v179, v235, v183
	v_fmac_f32_e32 v179, v228, v108
	v_fmac_f32_e32 v179, v229, v109
	v_fmac_f32_e32 v179, v230, v110
	v_fmac_f32_e32 v179, v231, v111
	ds_write_b32 v172, v179 offset:11264
	s_mov_b64 exec, s[40:41]
	ds_add_u32 v91, v92 offset:20
	s_mov_b64 exec, -1
	v_add_u32_e32 v170, 0x1080, v170
	v_add_u32_e32 v237, 0x1080, v237
	v_add_u32_e32 v95, 0x1080, v95
	s_waitcnt lgkmcnt(2)
	v_mfma_f32_16x16x4_f32 v[96:99], v22, v184, 0
	v_mfma_f32_16x16x4_f32 v[100:103], v23, v185, 0
	v_mfma_f32_16x16x4_f32 v[96:99], v24, v186, v[96:99]
	v_mfma_f32_16x16x4_f32 v[100:103], v25, v187, v[100:103]
	v_mul_f32_e32 v240, v238, v139
	v_rcp_f32_e32 v89, v240
	v_readfirstlane_b32 s0, v240
	v_mfma_f32_16x16x4_f32 v[96:99], v26, v188, v[96:99]
	v_mfma_f32_16x16x4_f32 v[100:103], v27, v189, v[100:103]
	v_mfma_f32_16x16x4_f32 v[96:99], v28, v190, v[96:99]
	v_mfma_f32_16x16x4_f32 v[100:103], v29, v191, v[100:103]
	ds_read_b32 v86, v87 offset:3072
	ds_read2_b32 v[62:63], v237 offset0:0 offset1:16
	ds_read2_b32 v[64:65], v237 offset0:32 offset1:48
	v_mfma_f32_16x16x4_f32 v[96:99], v30, v192, v[96:99]
	v_mfma_f32_16x16x4_f32 v[100:103], v31, v193, v[100:103]
	v_mfma_f32_16x16x4_f32 v[96:99], v32, v194, v[96:99]
	v_mfma_f32_16x16x4_f32 v[100:103], v33, v195, v[100:103]
	ds_read2_b32 v[66:67], v237 offset0:64 offset1:80
	ds_read2_b32 v[68:69], v237 offset0:96 offset1:112
	ds_read2st64_b32 v[74:75], v171 offset0:52 offset1:53
	v_mfma_f32_16x16x4_f32 v[96:99], v34, v196, v[96:99]
	v_mfma_f32_16x16x4_f32 v[100:103], v35, v197, v[100:103]
	v_mfma_f32_16x16x4_f32 v[96:99], v36, v198, v[96:99]
	v_mfma_f32_16x16x4_f32 v[100:103], v37, v199, v[100:103]
	ds_read2st64_b32 v[76:77], v171 offset0:54 offset1:55
	ds_read_b128 v[216:219], v93 offset:208
	ds_read_b128 v[220:223], v175 offset:464
	v_mfma_f32_16x16x4_f32 v[96:99], v38, v200, v[96:99]
	v_mfma_f32_16x16x4_f32 v[100:103], v39, v201, v[100:103]
	v_mfma_f32_16x16x4_f32 v[96:99], v40, v202, v[96:99]
	v_mfma_f32_16x16x4_f32 v[100:103], v41, v203, v[100:103]
	ds_read_b32 v235, v176 offset:464
	ds_read_b32 v236, v176 offset:720
	ds_read_b32 v234, v173 offset:3248
	v_mfma_f32_16x16x4_f32 v[96:99], v42, v204, v[96:99]
	v_mfma_f32_16x16x4_f32 v[100:103], v43, v205, v[100:103]
	v_mfma_f32_16x16x4_f32 v[96:99], v44, v206, v[96:99]
	v_mfma_f32_16x16x4_f32 v[100:103], v45, v207, v[100:103]
	ds_read_b64 v[232:233], v173 offset:3280
	ds_read_b128 v[224:227], v173 offset:3312
	ds_read_b128 v[228:231], v174 offset:3216
	v_mfma_f32_16x16x4_f32 v[96:99], v46, v208, v[96:99]
	v_mfma_f32_16x16x4_f32 v[100:103], v47, v209, v[100:103]
	v_mfma_f32_16x16x4_f32 v[96:99], v48, v210, v[96:99]
	v_mfma_f32_16x16x4_f32 v[100:103], v49, v211, v[100:103]
	v_mfma_f32_16x16x4_f32 v[96:99], v50, v212, v[96:99]
	v_mfma_f32_16x16x4_f32 v[100:103], v51, v213, v[100:103]
	v_mfma_f32_16x16x4_f32 v[96:99], v52, v214, v[96:99]
	v_mfma_f32_16x16x4_f32 v[100:103], v53, v215, v[100:103]
	s_nop 7
	s_nop 1
	v_pk_mul_f32 v[100:101], v[100:101], v[238:239] op_sel_hi:[1,0]
	v_pk_mul_f32 v[102:103], v[102:103], v[238:239] op_sel_hi:[1,0]
	v_pk_fma_f32 v[78:79], v[96:97], v[238:239], v[100:101] op_sel_hi:[1,0,1]
	v_pk_fma_f32 v[80:81], v[98:99], v[238:239], v[102:103] op_sel_hi:[1,0,1]
	v_pk_fma_f32 v[96:97], v[96:97], v[238:239], v[100:101] op_sel_hi:[1,0,1]
	v_pk_fma_f32 v[98:99], v[98:99], v[238:239], v[102:103] op_sel_hi:[1,0,1]
	s_nop 0
	v_permlane32_swap_b32_e32 v96, v78
	v_permlane32_swap_b32_e32 v97, v79
	v_permlane32_swap_b32_e32 v98, v80
	v_permlane32_swap_b32_e32 v99, v81
	v_mov_b32_e32 v82, v96
	v_mov_b32_e32 v83, v97
	v_mov_b32_e32 v84, v98
	v_mov_b32_e32 v85, v99
	s_nop 0
	v_permlane16_swap_b32_e32 v96, v82
	v_permlane16_swap_b32_e32 v97, v83
	v_permlane16_swap_b32_e32 v98, v84
	v_permlane16_swap_b32_e32 v99, v85
	v_fma_f32 v108, v132, v96, v70
	v_fma_f32 v109, v133, v97, v71
	v_fma_f32 v110, v134, v98, v72
	v_fma_f32 v111, v135, v99, v73
	v_fma_f32 v109, -v150, v108, v109
	v_fma_f32 v110, -v148, v108, v110
	v_fma_f32 v111, -v140, v108, v111
	v_fma_f32 v110, -v149, v109, v110
	v_fma_f32 v111, -v141, v109, v111
	v_fma_f32 v111, -v142, v110, v111
	v_cndmask_b32_e32 v182, v108, v109, vcc
	v_cndmask_b32_e64 v182, v182, v110, s[4:5]
	v_cndmask_b32_e64 v182, v182, v111, s[6:7]
	v_mul_f32_e32 v182, v152, v182
	s_cmp_lt_u32 s0, 0x2b800000
	s_cbranch_scc0 .Lgdn_nomat_6_0
	v_pk_mul_f32 v[184:185], v[184:185], v[240:241] op_sel_hi:[1,0]
	v_pk_mul_f32 v[186:187], v[186:187], v[240:241] op_sel_hi:[1,0]
	v_pk_mul_f32 v[188:189], v[188:189], v[240:241] op_sel_hi:[1,0]
	v_pk_mul_f32 v[190:191], v[190:191], v[240:241] op_sel_hi:[1,0]
	v_pk_mul_f32 v[192:193], v[192:193], v[240:241] op_sel_hi:[1,0]
	v_pk_mul_f32 v[194:195], v[194:195], v[240:241] op_sel_hi:[1,0]
	v_pk_mul_f32 v[196:197], v[196:197], v[240:241] op_sel_hi:[1,0]
	v_pk_mul_f32 v[198:199], v[198:199], v[240:241] op_sel_hi:[1,0]
	v_pk_mul_f32 v[200:201], v[200:201], v[240:241] op_sel_hi:[1,0]
	v_pk_mul_f32 v[202:203], v[202:203], v[240:241] op_sel_hi:[1,0]
	v_pk_mul_f32 v[204:205], v[204:205], v[240:241] op_sel_hi:[1,0]
	v_pk_mul_f32 v[206:207], v[206:207], v[240:241] op_sel_hi:[1,0]
	v_pk_mul_f32 v[208:209], v[208:209], v[240:241] op_sel_hi:[1,0]
	v_pk_mul_f32 v[210:211], v[210:211], v[240:241] op_sel_hi:[1,0]
	v_pk_mul_f32 v[212:213], v[212:213], v[240:241] op_sel_hi:[1,0]
	v_pk_mul_f32 v[214:215], v[214:215], v[240:241] op_sel_hi:[1,0]
	v_mov_b32_e32 v240, 1.0
	v_mov_b32_e32 v89, 1.0
.Lgdn_nomat_6_0:
	v_mov_b32_e32 v238, v240
	v_mul_f32_e32 v90, v182, v89
	s_nop 1
	v_mfma_f32_16x16x4_f32 v[184:187], v54, v90, v[184:187]
	v_mfma_f32_16x16x4_f32 v[188:191], v55, v90, v[188:191]
	v_mfma_f32_16x16x4_f32 v[192:195], v56, v90, v[192:195]
	v_mfma_f32_16x16x4_f32 v[196:199], v57, v90, v[196:199]
	v_mfma_f32_16x16x4_f32 v[200:203], v58, v90, v[200:203]
	v_mfma_f32_16x16x4_f32 v[204:207], v59, v90, v[204:207]
	v_mfma_f32_16x16x4_f32 v[208:211], v60, v90, v[208:211]
	v_mfma_f32_16x16x4_f32 v[212:215], v61, v90, v[212:215]
	v_pk_mul_f32 v[78:79], v[78:79], v[138:139] op_sel:[0,1] op_sel_hi:[1,1]
	v_pk_mul_f32 v[80:81], v[80:81], v[138:139] op_sel:[0,1] op_sel_hi:[1,1]
	v_cndmask_b32_e32 v183, v82, v83, vcc
	v_cndmask_b32_e64 v183, v183, v84, s[4:5]
	v_cndmask_b32_e64 v183, v183, v85, s[6:7]
	v_mul_f32_e32 v179, v151, v183
	v_fmac_f32_e32 v179, v144, v108
	v_fmac_f32_e32 v179, v145, v109
	v_fmac_f32_e32 v179, v146, v110
	v_fmac_f32_e32 v179, v147, v111
	ds_write_b32 v172, v179 offset:12288
	s_waitcnt lgkmcnt(1)
	v_mfma_f32_16x16x4_f32 v[96:99], v86, v182, v[78:81]
	s_nop 7
	v_mul_f32_e32 v240, v238, v223
	v_rcp_f32_e32 v89, v240
	v_readfirstlane_b32 s0, v240
	ds_read_b128 v[22:25], v169 offset:29568
	ds_read_b128 v[26:29], v169 offset:29632
	ds_read_b128 v[30:33], v169 offset:29696
	ds_read_b128 v[34:37], v169 offset:29760
	ds_read_b128 v[38:41], v169 offset:29824
	ds_read_b128 v[42:45], v169 offset:29888
	ds_read_b128 v[46:49], v169 offset:29952
	ds_read_b128 v[50:53], v169 offset:30016
	ds_read2_b32 v[54:55], v95 offset0:0 offset1:16
	ds_read2_b32 v[56:57], v95 offset0:32 offset1:48
	ds_read2_b32 v[58:59], v95 offset0:64 offset1:80
	ds_read2_b32 v[60:61], v95 offset0:96 offset1:112
	ds_read2st64_b32 v[70:71], v171 offset0:56 offset1:57
	ds_read2st64_b32 v[72:73], v171 offset0:58 offset1:59
	ds_read_b128 v[132:135], v93 offset:224
	ds_read_b128 v[136:139], v175 offset:480
	ds_read_b32 v151, v176 offset:480
	ds_read_b32 v152, v176 offset:736
	ds_read_b32 v150, v173 offset:3616
	ds_read_b64 v[148:149], v173 offset:3648
	ds_read_b128 v[140:143], v173 offset:3680
	ds_read_b128 v[144:147], v174 offset:3584
	v_mov_b32_e32 v82, v96
	v_mov_b32_e32 v83, v97
	v_mov_b32_e32 v84, v98
	v_mov_b32_e32 v85, v99
	s_nop 0
	v_permlane16_swap_b32_e32 v96, v82
	v_permlane16_swap_b32_e32 v97, v83
	v_permlane16_swap_b32_e32 v98, v84
	v_permlane16_swap_b32_e32 v99, v85
	v_fma_f32 v108, v216, v96, v74
	v_fma_f32 v109, v217, v97, v75
	v_fma_f32 v110, v218, v98, v76
	v_fma_f32 v111, v219, v99, v77
	v_fma_f32 v109, -v234, v108, v109
	v_fma_f32 v110, -v232, v108, v110
	v_fma_f32 v111, -v224, v108, v111
	v_fma_f32 v110, -v233, v109, v110
	v_fma_f32 v111, -v225, v109, v111
	v_fma_f32 v111, -v226, v110, v111
	v_cndmask_b32_e32 v182, v108, v109, vcc
	v_cndmask_b32_e64 v182, v182, v110, s[4:5]
	v_cndmask_b32_e64 v182, v182, v111, s[6:7]
	v_mul_f32_e32 v182, v236, v182
	s_cmp_lt_u32 s0, 0x2b800000
	s_cbranch_scc0 .Lgdn_nomat_6_1
	v_pk_mul_f32 v[184:185], v[184:185], v[240:241] op_sel_hi:[1,0]
	v_pk_mul_f32 v[186:187], v[186:187], v[240:241] op_sel_hi:[1,0]
	v_pk_mul_f32 v[188:189], v[188:189], v[240:241] op_sel_hi:[1,0]
	v_pk_mul_f32 v[190:191], v[190:191], v[240:241] op_sel_hi:[1,0]
	v_pk_mul_f32 v[192:193], v[192:193], v[240:241] op_sel_hi:[1,0]
	v_pk_mul_f32 v[194:195], v[194:195], v[240:241] op_sel_hi:[1,0]
	v_pk_mul_f32 v[196:197], v[196:197], v[240:241] op_sel_hi:[1,0]
	v_pk_mul_f32 v[198:199], v[198:199], v[240:241] op_sel_hi:[1,0]
	v_pk_mul_f32 v[200:201], v[200:201], v[240:241] op_sel_hi:[1,0]
	v_pk_mul_f32 v[202:203], v[202:203], v[240:241] op_sel_hi:[1,0]
	v_pk_mul_f32 v[204:205], v[204:205], v[240:241] op_sel_hi:[1,0]
	v_pk_mul_f32 v[206:207], v[206:207], v[240:241] op_sel_hi:[1,0]
	v_pk_mul_f32 v[208:209], v[208:209], v[240:241] op_sel_hi:[1,0]
	v_pk_mul_f32 v[210:211], v[210:211], v[240:241] op_sel_hi:[1,0]
	v_pk_mul_f32 v[212:213], v[212:213], v[240:241] op_sel_hi:[1,0]
	v_pk_mul_f32 v[214:215], v[214:215], v[240:241] op_sel_hi:[1,0]
	v_mov_b32_e32 v240, 1.0
	v_mov_b32_e32 v89, 1.0
.Lgdn_nomat_6_1:
	v_mov_b32_e32 v238, v240
	v_mul_f32_e32 v90, v182, v89
	s_nop 1
	v_mfma_f32_16x16x4_f32 v[184:187], v62, v90, v[184:187]
	v_mfma_f32_16x16x4_f32 v[188:191], v63, v90, v[188:191]
	v_mfma_f32_16x16x4_f32 v[192:195], v64, v90, v[192:195]
	v_mfma_f32_16x16x4_f32 v[196:199], v65, v90, v[196:199]
	v_mfma_f32_16x16x4_f32 v[200:203], v66, v90, v[200:203]
	v_mfma_f32_16x16x4_f32 v[204:207], v67, v90, v[204:207]
	v_mfma_f32_16x16x4_f32 v[208:211], v68, v90, v[208:211]
	v_mfma_f32_16x16x4_f32 v[212:215], v69, v90, v[212:215]
	v_cndmask_b32_e32 v183, v82, v83, vcc
	v_cndmask_b32_e64 v183, v183, v84, s[4:5]
	v_cndmask_b32_e64 v183, v183, v85, s[6:7]
	v_mul_f32_e32 v179, v235, v183
	v_fmac_f32_e32 v179, v228, v108
	v_fmac_f32_e32 v179, v229, v109
	v_fmac_f32_e32 v179, v230, v110
	v_fmac_f32_e32 v179, v231, v111
	ds_write_b32 v172, v179 offset:13312
	s_mov_b64 exec, s[40:41]
	ds_add_u32 v91, v92 offset:24
	s_mov_b64 exec, -1
	v_add_u32_e32 v170, 0x1080, v170
	v_add_u32_e32 v237, 0x1080, v237
	v_add_u32_e32 v95, 0x1080, v95
	s_waitcnt lgkmcnt(2)
	v_mfma_f32_16x16x4_f32 v[96:99], v22, v184, 0
	v_mfma_f32_16x16x4_f32 v[100:103], v23, v185, 0
	v_mfma_f32_16x16x4_f32 v[96:99], v24, v186, v[96:99]
	v_mfma_f32_16x16x4_f32 v[100:103], v25, v187, v[100:103]
	v_mul_f32_e32 v240, v238, v139
	v_rcp_f32_e32 v89, v240
	v_readfirstlane_b32 s0, v240
	v_mfma_f32_16x16x4_f32 v[96:99], v26, v188, v[96:99]
	v_mfma_f32_16x16x4_f32 v[100:103], v27, v189, v[100:103]
	v_mfma_f32_16x16x4_f32 v[96:99], v28, v190, v[96:99]
	v_mfma_f32_16x16x4_f32 v[100:103], v29, v191, v[100:103]
	ds_read_b32 v86, v87 offset:3584
	ds_read2_b32 v[62:63], v237 offset0:0 offset1:16
	ds_read2_b32 v[64:65], v237 offset0:32 offset1:48
	v_mfma_f32_16x16x4_f32 v[96:99], v30, v192, v[96:99]
	v_mfma_f32_16x16x4_f32 v[100:103], v31, v193, v[100:103]
	v_mfma_f32_16x16x4_f32 v[96:99], v32, v194, v[96:99]
	v_mfma_f32_16x16x4_f32 v[100:103], v33, v195, v[100:103]
	ds_read2_b32 v[66:67], v237 offset0:64 offset1:80
	ds_read2_b32 v[68:69], v237 offset0:96 offset1:112
	ds_read2st64_b32 v[74:75], v171 offset0:60 offset1:61
	v_mfma_f32_16x16x4_f32 v[96:99], v34, v196, v[96:99]
	v_mfma_f32_16x16x4_f32 v[100:103], v35, v197, v[100:103]
	v_mfma_f32_16x16x4_f32 v[96:99], v36, v198, v[96:99]
	v_mfma_f32_16x16x4_f32 v[100:103], v37, v199, v[100:103]
	ds_read2st64_b32 v[76:77], v171 offset0:62 offset1:63
	ds_read_b128 v[216:219], v93 offset:240
	ds_read_b128 v[220:223], v175 offset:496
	v_mfma_f32_16x16x4_f32 v[96:99], v38, v200, v[96:99]
	v_mfma_f32_16x16x4_f32 v[100:103], v39, v201, v[100:103]
	v_mfma_f32_16x16x4_f32 v[96:99], v40, v202, v[96:99]
	v_mfma_f32_16x16x4_f32 v[100:103], v41, v203, v[100:103]
	ds_read_b32 v235, v176 offset:496
	ds_read_b32 v236, v176 offset:752
	ds_read_b32 v234, v173 offset:3760
	v_mfma_f32_16x16x4_f32 v[96:99], v42, v204, v[96:99]
	v_mfma_f32_16x16x4_f32 v[100:103], v43, v205, v[100:103]
	v_mfma_f32_16x16x4_f32 v[96:99], v44, v206, v[96:99]
	v_mfma_f32_16x16x4_f32 v[100:103], v45, v207, v[100:103]
	ds_read_b64 v[232:233], v173 offset:3792
	ds_read_b128 v[224:227], v173 offset:3824
	ds_read_b128 v[228:231], v174 offset:3728
	v_mfma_f32_16x16x4_f32 v[96:99], v46, v208, v[96:99]
	v_mfma_f32_16x16x4_f32 v[100:103], v47, v209, v[100:103]
	v_mfma_f32_16x16x4_f32 v[96:99], v48, v210, v[96:99]
	v_mfma_f32_16x16x4_f32 v[100:103], v49, v211, v[100:103]
	v_mfma_f32_16x16x4_f32 v[96:99], v50, v212, v[96:99]
	v_mfma_f32_16x16x4_f32 v[100:103], v51, v213, v[100:103]
	v_mfma_f32_16x16x4_f32 v[96:99], v52, v214, v[96:99]
	v_mfma_f32_16x16x4_f32 v[100:103], v53, v215, v[100:103]
	s_nop 7
	s_nop 1
	v_pk_mul_f32 v[100:101], v[100:101], v[238:239] op_sel_hi:[1,0]
	v_pk_mul_f32 v[102:103], v[102:103], v[238:239] op_sel_hi:[1,0]
	v_pk_fma_f32 v[78:79], v[96:97], v[238:239], v[100:101] op_sel_hi:[1,0,1]
	v_pk_fma_f32 v[80:81], v[98:99], v[238:239], v[102:103] op_sel_hi:[1,0,1]
	v_pk_fma_f32 v[96:97], v[96:97], v[238:239], v[100:101] op_sel_hi:[1,0,1]
	v_pk_fma_f32 v[98:99], v[98:99], v[238:239], v[102:103] op_sel_hi:[1,0,1]
	s_nop 0
	v_permlane32_swap_b32_e32 v96, v78
	v_permlane32_swap_b32_e32 v97, v79
	v_permlane32_swap_b32_e32 v98, v80
	v_permlane32_swap_b32_e32 v99, v81
	v_mov_b32_e32 v82, v96
	v_mov_b32_e32 v83, v97
	v_mov_b32_e32 v84, v98
	v_mov_b32_e32 v85, v99
	s_nop 0
	v_permlane16_swap_b32_e32 v96, v82
	v_permlane16_swap_b32_e32 v97, v83
	v_permlane16_swap_b32_e32 v98, v84
	v_permlane16_swap_b32_e32 v99, v85
	v_fma_f32 v108, v132, v96, v70
	v_fma_f32 v109, v133, v97, v71
	v_fma_f32 v110, v134, v98, v72
	v_fma_f32 v111, v135, v99, v73
	v_fma_f32 v109, -v150, v108, v109
	v_fma_f32 v110, -v148, v108, v110
	v_fma_f32 v111, -v140, v108, v111
	v_fma_f32 v110, -v149, v109, v110
	v_fma_f32 v111, -v141, v109, v111
	v_fma_f32 v111, -v142, v110, v111
	v_cndmask_b32_e32 v182, v108, v109, vcc
	v_cndmask_b32_e64 v182, v182, v110, s[4:5]
	v_cndmask_b32_e64 v182, v182, v111, s[6:7]
	v_mul_f32_e32 v182, v152, v182
	s_cmp_lt_u32 s0, 0x2b800000
	s_cbranch_scc0 .Lgdn_nomat_7_0
	v_pk_mul_f32 v[184:185], v[184:185], v[240:241] op_sel_hi:[1,0]
	v_pk_mul_f32 v[186:187], v[186:187], v[240:241] op_sel_hi:[1,0]
	v_pk_mul_f32 v[188:189], v[188:189], v[240:241] op_sel_hi:[1,0]
	v_pk_mul_f32 v[190:191], v[190:191], v[240:241] op_sel_hi:[1,0]
	v_pk_mul_f32 v[192:193], v[192:193], v[240:241] op_sel_hi:[1,0]
	v_pk_mul_f32 v[194:195], v[194:195], v[240:241] op_sel_hi:[1,0]
	v_pk_mul_f32 v[196:197], v[196:197], v[240:241] op_sel_hi:[1,0]
	v_pk_mul_f32 v[198:199], v[198:199], v[240:241] op_sel_hi:[1,0]
	v_pk_mul_f32 v[200:201], v[200:201], v[240:241] op_sel_hi:[1,0]
	v_pk_mul_f32 v[202:203], v[202:203], v[240:241] op_sel_hi:[1,0]
	v_pk_mul_f32 v[204:205], v[204:205], v[240:241] op_sel_hi:[1,0]
	v_pk_mul_f32 v[206:207], v[206:207], v[240:241] op_sel_hi:[1,0]
	v_pk_mul_f32 v[208:209], v[208:209], v[240:241] op_sel_hi:[1,0]
	v_pk_mul_f32 v[210:211], v[210:211], v[240:241] op_sel_hi:[1,0]
	v_pk_mul_f32 v[212:213], v[212:213], v[240:241] op_sel_hi:[1,0]
	v_pk_mul_f32 v[214:215], v[214:215], v[240:241] op_sel_hi:[1,0]
	v_mov_b32_e32 v240, 1.0
	v_mov_b32_e32 v89, 1.0
.Lgdn_nomat_7_0:
	v_mov_b32_e32 v238, v240
	v_mul_f32_e32 v90, v182, v89
	s_nop 1
	v_mfma_f32_16x16x4_f32 v[184:187], v54, v90, v[184:187]
	v_mfma_f32_16x16x4_f32 v[188:191], v55, v90, v[188:191]
	v_mfma_f32_16x16x4_f32 v[192:195], v56, v90, v[192:195]
	v_mfma_f32_16x16x4_f32 v[196:199], v57, v90, v[196:199]
	v_mfma_f32_16x16x4_f32 v[200:203], v58, v90, v[200:203]
	v_mfma_f32_16x16x4_f32 v[204:207], v59, v90, v[204:207]
	v_mfma_f32_16x16x4_f32 v[208:211], v60, v90, v[208:211]
	v_mfma_f32_16x16x4_f32 v[212:215], v61, v90, v[212:215]
	v_pk_mul_f32 v[78:79], v[78:79], v[138:139] op_sel:[0,1] op_sel_hi:[1,1]
	v_pk_mul_f32 v[80:81], v[80:81], v[138:139] op_sel:[0,1] op_sel_hi:[1,1]
	v_cndmask_b32_e32 v183, v82, v83, vcc
	v_cndmask_b32_e64 v183, v183, v84, s[4:5]
	v_cndmask_b32_e64 v183, v183, v85, s[6:7]
	v_mul_f32_e32 v179, v151, v183
	v_fmac_f32_e32 v179, v144, v108
	v_fmac_f32_e32 v179, v145, v109
	v_fmac_f32_e32 v179, v146, v110
	v_fmac_f32_e32 v179, v147, v111
	ds_write_b32 v172, v179 offset:14336
	s_waitcnt lgkmcnt(1)
	v_mfma_f32_16x16x4_f32 v[96:99], v86, v182, v[78:81]
	s_nop 7
	v_mul_f32_e32 v240, v238, v223
	v_rcp_f32_e32 v89, v240
	v_readfirstlane_b32 s0, v240
	ds_read_b128 v[22:25], v169 offset:33792
	ds_read_b128 v[26:29], v169 offset:33856
	ds_read_b128 v[30:33], v169 offset:33920
	ds_read_b128 v[34:37], v169 offset:33984
	ds_read_b128 v[38:41], v169 offset:34048
	ds_read_b128 v[42:45], v169 offset:34112
	ds_read_b128 v[46:49], v169 offset:34176
	ds_read_b128 v[50:53], v169 offset:34240
	ds_read2_b32 v[54:55], v95 offset0:0 offset1:16
	ds_read2_b32 v[56:57], v95 offset0:32 offset1:48
	ds_read2_b32 v[58:59], v95 offset0:64 offset1:80
	ds_read2_b32 v[60:61], v95 offset0:96 offset1:112
	ds_read2st64_b32 v[70:71], v171 offset0:64 offset1:65
	ds_read2st64_b32 v[72:73], v171 offset0:66 offset1:67
	ds_read_b128 v[132:135], v93 offset:256
	ds_read_b128 v[136:139], v175 offset:512
	ds_read_b32 v151, v176 offset:512
	ds_read_b32 v152, v176 offset:768
	ds_read_b32 v150, v173 offset:4128
	ds_read_b64 v[148:149], v173 offset:4160
	ds_read_b128 v[140:143], v173 offset:4192
	ds_read_b128 v[144:147], v174 offset:4096
	v_mov_b32_e32 v82, v96
	v_mov_b32_e32 v83, v97
	v_mov_b32_e32 v84, v98
	v_mov_b32_e32 v85, v99
	s_nop 0
	v_permlane16_swap_b32_e32 v96, v82
	v_permlane16_swap_b32_e32 v97, v83
	v_permlane16_swap_b32_e32 v98, v84
	v_permlane16_swap_b32_e32 v99, v85
	v_fma_f32 v108, v216, v96, v74
	v_fma_f32 v109, v217, v97, v75
	v_fma_f32 v110, v218, v98, v76
	v_fma_f32 v111, v219, v99, v77
	v_fma_f32 v109, -v234, v108, v109
	v_fma_f32 v110, -v232, v108, v110
	v_fma_f32 v111, -v224, v108, v111
	v_fma_f32 v110, -v233, v109, v110
	v_fma_f32 v111, -v225, v109, v111
	v_fma_f32 v111, -v226, v110, v111
	v_cndmask_b32_e32 v182, v108, v109, vcc
	v_cndmask_b32_e64 v182, v182, v110, s[4:5]
	v_cndmask_b32_e64 v182, v182, v111, s[6:7]
	v_mul_f32_e32 v182, v236, v182
	s_cmp_lt_u32 s0, 0x2b800000
	s_cbranch_scc0 .Lgdn_nomat_7_1
	v_pk_mul_f32 v[184:185], v[184:185], v[240:241] op_sel_hi:[1,0]
	v_pk_mul_f32 v[186:187], v[186:187], v[240:241] op_sel_hi:[1,0]
	v_pk_mul_f32 v[188:189], v[188:189], v[240:241] op_sel_hi:[1,0]
	v_pk_mul_f32 v[190:191], v[190:191], v[240:241] op_sel_hi:[1,0]
	v_pk_mul_f32 v[192:193], v[192:193], v[240:241] op_sel_hi:[1,0]
	v_pk_mul_f32 v[194:195], v[194:195], v[240:241] op_sel_hi:[1,0]
	v_pk_mul_f32 v[196:197], v[196:197], v[240:241] op_sel_hi:[1,0]
	v_pk_mul_f32 v[198:199], v[198:199], v[240:241] op_sel_hi:[1,0]
	v_pk_mul_f32 v[200:201], v[200:201], v[240:241] op_sel_hi:[1,0]
	v_pk_mul_f32 v[202:203], v[202:203], v[240:241] op_sel_hi:[1,0]
	v_pk_mul_f32 v[204:205], v[204:205], v[240:241] op_sel_hi:[1,0]
	v_pk_mul_f32 v[206:207], v[206:207], v[240:241] op_sel_hi:[1,0]
	v_pk_mul_f32 v[208:209], v[208:209], v[240:241] op_sel_hi:[1,0]
	v_pk_mul_f32 v[210:211], v[210:211], v[240:241] op_sel_hi:[1,0]
	v_pk_mul_f32 v[212:213], v[212:213], v[240:241] op_sel_hi:[1,0]
	v_pk_mul_f32 v[214:215], v[214:215], v[240:241] op_sel_hi:[1,0]
	v_mov_b32_e32 v240, 1.0
	v_mov_b32_e32 v89, 1.0

.LBB0_564:
	v_mov_b32_e32 v78, v75
	v_mov_b32_e32 v76, v77
	s_and_b32 s3, s40, 1
	v_add_u32_e32 v28, s72, v76
	v_ashrrev_i32_e32 v29, 31, v28
	v_lshlrev_b64 v[10:11], 2, v[28:29]
	v_lshl_add_u64 v[2:3], s[42:43], 0, v[10:11]
	global_load_dword v5, v[2:3], off
	global_load_dword v4, v[2:3], off offset:2048
	v_add_co_u32_e32 v2, vcc, s88, v2
	v_lshl_add_u64 v[6:7], s[44:45], 0, v[10:11]
	s_nop 0
	v_addc_co_u32_e32 v3, vcc, 0, v3, vcc
	v_lshl_add_u64 v[8:9], s[48:49], 0, v[10:11]
	global_load_dword v9, v[8:9], off
	s_nop 0
	global_load_dword v8, v[6:7], off
	s_nop 0
	global_load_dword v7, v[2:3], off
	v_lshl_add_u64 v[2:3], s[52:53], 0, v[10:11]
	global_load_dword v6, v[2:3], off
	v_lshl_add_u64 v[2:3], s[54:55], 0, v[10:11]
	global_load_dword v3, v[2:3], off
	v_lshl_add_u64 v[10:11], s[56:57], 0, v[10:11]
	global_load_dword v2, v[10:11], off
	s_mov_b64 s[0:1], src_shared_base
	s_cmp_lg_u32 0, -1
	v_sub_f32_e32 v14, v35, v46
	s_cselect_b32 s4, s1, 0
	s_cselect_b32 s5, 0, 0
	v_mad_u64_u32 v[10:11], s[0:1], v78, s87, v[76:77]
	s_add_u32 s0, s5, 0x11800
	v_lshl_add_u32 v16, v10, 2, 0
	s_addc_u32 s1, s4, 0
	s_cmp_lg_u64 s[0:1], 0
	s_cselect_b32 s6, s0, -1
	s_add_i32 s7, 0, 0x17800
	s_add_u32 s0, s5, 0x23800
	s_addc_u32 s1, s4, 0
	s_cmp_lg_u64 s[0:1], 0
	s_cselect_b32 s0, s0, -1
	s_add_i32 s1, 0, 0x1b800
	s_cmp_eq_u32 s3, 0
	s_cselect_b32 s16, s0, s1
	v_sub_f32_e32 v13, v106, v44
	s_cselect_b32 s41, s6, s7
	v_sub_f32_e32 v15, v34, v48
	v_lshl_add_u32 v12, v76, 2, s41
	v_lshlrev_b32_e32 v26, 3, v78
	v_cmp_eq_u32_e32 vcc, 0, v76
	s_waitcnt vmcnt(7)
	v_fma_f32 v13, v13, v5, v44
	s_waitcnt vmcnt(6)
	v_fma_f32 v14, v14, v4, v46
	s_waitcnt vmcnt(5)
	v_add_f32_e32 v10, v50, v9
	s_waitcnt vmcnt(4)
	v_add_f32_e32 v11, v107, v8
	v_mul_f32_e32 v10, 0xbfb8aa3b, v10
	v_mul_f32_e32 v11, 0xbfb8aa3b, v11
	s_waitcnt vmcnt(2)
	v_mul_f32_e32 v17, v14, v6
	v_exp_f32_e32 v10, v10
	v_exp_f32_e32 v11, v11
	v_mul_f32_e32 v18, v17, v17
	v_fma_f32 v15, v15, v7, v48
	v_add_f32_e32 v10, 1.0, v10
	v_mov_b32_dpp v18, v18 quad_perm:[1,0,3,2] row_mask:0xf bank_mask:0xf bound_ctrl:1
	v_fmac_f32_e32 v18, v17, v17
	v_add_f32_e32 v11, 1.0, v11
	v_rcp_f32_e32 v19, v10
	v_add_f32_dpp v18, v18, v18 quad_perm:[2,3,0,1] row_mask:0xf bank_mask:0xf bound_ctrl:1
	v_rcp_f32_e32 v20, v11
	s_nop 0
	v_add_f32_dpp v18, v18, v18 row_half_mirror row_mask:0xf bank_mask:0xf bound_ctrl:1
	s_nop 1
	v_add_f32_dpp v10, v18, v18 row_mirror row_mask:0xf bank_mask:0xf bound_ctrl:1
	v_mul_f32_e32 v18, 0xbf1b4598, v20
	v_readlane_b32 s3, v10, 16
	v_readlane_b32 s4, v10, 48
	v_readlane_b32 s0, v10, 0
	v_readlane_b32 s1, v10, 32
	v_mov_b32_e32 v10, s3
	v_mov_b32_e32 v11, s4
	v_pk_add_f32 v[10:11], s[0:1], v[10:11]
	v_mul_f32_e32 v18, 0x3fb8aa3b, v18
	v_add_f32_e32 v10, v10, v11
	v_add_f32_e32 v11, -1.0, v19
	v_add_f32_e32 v10, 0x2b8cbccc, v10
	s_waitcnt vmcnt(1)
	v_fma_f32 v20, v3, v11, 1.0
	v_exp_f32_e32 v11, v18
	v_mul_f32_e32 v18, 0x4b800000, v10
	v_cmp_gt_f32_e64 s[0:1], s91, v10
	v_mul_f32_e32 v14, v14, v20
	s_nop 0
	v_cndmask_b32_e64 v10, v10, v18, s[0:1]
	v_rsq_f32_e32 v10, v10
	v_mul_f32_e32 v18, v13, v14
	s_waitcnt vmcnt(0)
	v_mul_f32_e32 v20, v2, v18
	v_mul_f32_e32 v13, v13, v11
	v_mul_f32_e32 v21, 0x45800000, v10
	v_mov_b32_dpp v20, v20 quad_perm:[1,0,3,2] row_mask:0xf bank_mask:0xf bound_ctrl:1
	v_fmac_f32_e32 v20, v2, v18
	v_rcp_f32_e32 v18, v11
	v_cndmask_b32_e64 v10, v10, v21, s[0:1]
	v_mul_f32_e64 v10, v17, -v10
	v_add_f32_dpp v20, v20, v20 quad_perm:[2,3,0,1] row_mask:0xf bank_mask:0xf bound_ctrl:1
	ds_write2st64_b32 v16, v10, v13 offset1:68
	v_mul_f32_e64 v10, v19, -v10
	v_add_f32_dpp v20, v20, v20 row_half_mirror row_mask:0xf bank_mask:0xf bound_ctrl:1
	v_mul_f32_e32 v14, v18, v14
	v_mul_f32_e32 v10, v18, v10
	v_add_f32_dpp v20, v20, v20 row_mirror row_mask:0xf bank_mask:0xf bound_ctrl:1
	ds_write2st64_b32 v16, v10, v14 offset0:136 offset1:204
	v_lshl_add_u32 v10, v78, 11, v12
	v_readlane_b32 s0, v20, 0
	v_readlane_b32 s3, v20, 16
	v_readlane_b32 s1, v20, 32
	v_readlane_b32 s6, v20, 48
	ds_write_b32 v10, v15
	v_lshl_add_u32 v10, v26, 2, s16
	s_and_saveexec_b64 s[4:5], vcc
	v_mov_b32_e32 v14, s3
	v_mov_b32_e32 v15, s6
	v_pk_add_f32 v[14:15], s[0:1], v[14:15]
	s_nop 0
	v_add_f32_e32 v13, v14, v15
	ds_write_b32 v10, v13
	s_or_b64 exec, exec, s[4:5]
	v_add_f32_e32 v15, v51, v9
	v_mul_f32_e32 v15, 0xbfb8aa3b, v15
	v_add_f32_e32 v18, v108, v8
	v_exp_f32_e32 v15, v15
	v_mul_f32_e32 v18, 0xbfb8aa3b, v18
	v_exp_f32_e32 v18, v18
	v_sub_f32_e32 v13, v44, v1
	v_fma_f32 v17, v13, v5, v1
	v_sub_f32_e32 v13, v46, v45
	v_sub_f32_e32 v14, v48, v47
	v_fma_f32 v13, v13, v4, v45
	v_fma_f32 v19, v14, v7, v47
	v_add_f32_e32 v14, 1.0, v15
	v_rcp_f32_e32 v20, v14
	v_add_f32_e32 v14, 1.0, v18
	v_mul_f32_e32 v21, v13, v6
	v_rcp_f32_e32 v18, v14
	v_mul_f32_e32 v14, v21, v21
	v_or_b32_e32 v16, 1, v26
	s_nop 0
	v_mov_b32_dpp v14, v14 quad_perm:[1,0,3,2] row_mask:0xf bank_mask:0xf bound_ctrl:1
	v_fmac_f32_e32 v14, v21, v21
	s_nop 1
	v_add_f32_dpp v14, v14, v14 quad_perm:[2,3,0,1] row_mask:0xf bank_mask:0xf bound_ctrl:1
	s_nop 1
	v_add_f32_dpp v14, v14, v14 row_half_mirror row_mask:0xf bank_mask:0xf bound_ctrl:1
	s_nop 1
	v_add_f32_dpp v14, v14, v14 row_mirror row_mask:0xf bank_mask:0xf bound_ctrl:1
	s_nop 0
	v_readlane_b32 s3, v14, 16
	v_readlane_b32 s4, v14, 48
	v_readlane_b32 s0, v14, 0
	v_readlane_b32 s1, v14, 32
	v_mov_b32_e32 v14, s3
	v_mov_b32_e32 v15, s4
	v_pk_add_f32 v[14:15], s[0:1], v[14:15]
	s_movk_i32 s4, 0x44
	v_add_f32_e32 v14, v14, v15
	v_add_f32_e32 v14, 0x2b8cbccc, v14
	v_mul_f32_e32 v15, 0x4b800000, v14
	v_cmp_gt_f32_e64 s[0:1], s91, v14
	s_nop 1
	v_cndmask_b32_e64 v14, v14, v15, s[0:1]
	v_rsq_f32_e32 v14, v14
	v_mul_f32_e32 v15, 0xbf1b4598, v18
	v_mul_f32_e32 v15, 0x3fb8aa3b, v15
	v_exp_f32_e32 v15, v15
	v_mul_f32_e32 v18, 0x45800000, v14
	v_cndmask_b32_e64 v14, v14, v18, s[0:1]
	v_mul_f32_e32 v18, v21, v14
	v_add_f32_e32 v14, -1.0, v20
	v_fma_f32 v14, v3, v14, 1.0
	v_mul_f32_e32 v21, v13, v14
	v_mul_f32_e32 v13, v17, v21
	v_mul_f32_e32 v14, v2, v13
	v_mul_f32_e64 v23, v11, -v18
	s_nop 0
	v_mov_b32_dpp v14, v14 quad_perm:[1,0,3,2] row_mask:0xf bank_mask:0xf bound_ctrl:1
	v_fmac_f32_e32 v14, v2, v13
	s_nop 1
	v_add_f32_dpp v13, v14, v14 quad_perm:[2,3,0,1] row_mask:0xf bank_mask:0xf bound_ctrl:1
	s_nop 1
	v_add_f32_dpp v13, v13, v13 row_half_mirror row_mask:0xf bank_mask:0xf bound_ctrl:1
	s_nop 1
	v_add_f32_dpp v13, v13, v13 row_mirror row_mask:0xf bank_mask:0xf bound_ctrl:1
	s_nop 0
	v_readlane_b32 s0, v13, 0
	v_readlane_b32 s3, v13, 16
	v_readlane_b32 s1, v13, 32
	v_readlane_b32 s6, v13, 48
	v_mul_f32_e32 v13, v11, v15
	v_rcp_f32_e32 v22, v13
	v_mad_u64_u32 v[14:15], s[4:5], v16, s4, v[76:77]
	v_lshl_add_u32 v11, v14, 2, 0
	v_mul_f32_e32 v14, v17, v13
	ds_write2st64_b32 v11, v23, v14 offset1:68
	v_mul_f32_e32 v14, v20, v18
	v_mul_f32_e32 v14, v22, v14
	v_mul_f32_e32 v15, v22, v21
	ds_write2st64_b32 v11, v14, v15 offset0:136 offset1:204
	v_lshl_add_u32 v14, v16, 8, v12
	ds_write_b32 v14, v19
	s_and_saveexec_b64 s[4:5], vcc
	v_mov_b32_e32 v14, s3
	v_mov_b32_e32 v15, s6
	v_pk_add_f32 v[14:15], s[0:1], v[14:15]
	s_nop 0
	v_add_f32_e32 v14, v14, v15
	ds_write_b32 v10, v14 offset:4
	s_or_b64 exec, exec, s[4:5]
	v_add_f32_e32 v15, v58, v9
	v_mul_f32_e32 v15, 0xbfb8aa3b, v15
	v_add_f32_e32 v18, v109, v8
	v_exp_f32_e32 v15, v15
	v_mul_f32_e32 v18, 0xbfb8aa3b, v18
	v_sub_f32_e32 v14, v1, v52
	v_exp_f32_e32 v18, v18
	v_fma_f32 v16, v14, v5, v52
	v_sub_f32_e32 v14, v45, v54
	v_fma_f32 v17, v14, v4, v54
	v_sub_f32_e32 v14, v47, v56
	v_fma_f32 v19, v14, v7, v56
	v_add_f32_e32 v14, 1.0, v15
	v_rcp_f32_e32 v20, v14
	v_add_f32_e32 v14, 1.0, v18
	v_mul_f32_e32 v21, v17, v6
	v_rcp_f32_e32 v18, v14
	v_mul_f32_e32 v14, v21, v21
	v_lshl_add_u32 v12, v26, 8, v12
	s_nop 0
	v_mov_b32_dpp v14, v14 quad_perm:[1,0,3,2] row_mask:0xf bank_mask:0xf bound_ctrl:1
	v_fmac_f32_e32 v14, v21, v21
	s_nop 1
	v_add_f32_dpp v14, v14, v14 quad_perm:[2,3,0,1] row_mask:0xf bank_mask:0xf bound_ctrl:1
	s_nop 1
	v_add_f32_dpp v14, v14, v14 row_half_mirror row_mask:0xf bank_mask:0xf bound_ctrl:1
	s_nop 1
	v_add_f32_dpp v14, v14, v14 row_mirror row_mask:0xf bank_mask:0xf bound_ctrl:1
	s_nop 0
	v_readlane_b32 s3, v14, 16
	v_readlane_b32 s4, v14, 48
	v_readlane_b32 s0, v14, 0
	v_readlane_b32 s1, v14, 32
	v_mov_b32_e32 v14, s3
	v_mov_b32_e32 v15, s4
	v_pk_add_f32 v[14:15], s[0:1], v[14:15]
	s_nop 0
	v_add_f32_e32 v14, v14, v15
	v_add_f32_e32 v14, 0x2b8cbccc, v14
	v_mul_f32_e32 v15, 0x4b800000, v14
	v_cmp_gt_f32_e64 s[0:1], s91, v14
	s_nop 1
	v_cndmask_b32_e64 v14, v14, v15, s[0:1]
	v_rsq_f32_e32 v14, v14
	v_mul_f32_e32 v15, 0xbf1b4598, v18
	v_mul_f32_e32 v15, 0x3fb8aa3b, v15
	v_exp_f32_e32 v15, v15
	v_mul_f32_e32 v18, 0x45800000, v14
	v_cndmask_b32_e64 v14, v14, v18, s[0:1]
	v_mul_f32_e32 v18, v21, v14
	v_add_f32_e32 v14, -1.0, v20
	v_fma_f32 v14, v3, v14, 1.0
	v_mul_f32_e32 v17, v17, v14
	v_mul_f32_e32 v14, v16, v17
	v_mul_f32_e32 v21, v2, v14
	s_nop 1
	v_mov_b32_dpp v21, v21 quad_perm:[1,0,3,2] row_mask:0xf bank_mask:0xf bound_ctrl:1
	v_fmac_f32_e32 v21, v2, v14
	s_nop 1
	v_add_f32_dpp v14, v21, v21 quad_perm:[2,3,0,1] row_mask:0xf bank_mask:0xf bound_ctrl:1
	v_add_u32_e32 v21, 16, v11
	s_nop 0
	v_add_f32_dpp v14, v14, v14 row_half_mirror row_mask:0xf bank_mask:0xf bound_ctrl:1
	s_nop 1
	v_add_f32_dpp v14, v14, v14 row_mirror row_mask:0xf bank_mask:0xf bound_ctrl:1
	s_nop 0
	v_readlane_b32 s0, v14, 0
	v_readlane_b32 s3, v14, 16
	v_readlane_b32 s1, v14, 32
	v_readlane_b32 s6, v14, 48
	v_mul_f32_e32 v14, v15, v13
	v_rcp_f32_e32 v15, v14
	v_mul_f32_e64 v13, v13, -v18
	v_mul_f32_e32 v16, v16, v14
	ds_write2st64_b32 v21, v13, v16 offset0:1 offset1:69
	v_mul_f32_e32 v13, v20, v18
	v_mul_f32_e32 v13, v15, v13
	v_mul_f32_e32 v15, v17, v15
	ds_write2st64_b32 v21, v13, v15 offset0:137 offset1:205
	ds_write_b32 v12, v19 offset:512
	s_and_saveexec_b64 s[4:5], vcc
	v_mov_b32_e32 v16, s3
	v_mov_b32_e32 v17, s6
	v_pk_add_f32 v[16:17], s[0:1], v[16:17]
	s_nop 0
	v_add_f32_e32 v13, v16, v17
	ds_write_b32 v10, v13 offset:8
	s_or_b64 exec, exec, s[4:5]
	v_add_f32_e32 v17, v57, v9
	v_mul_f32_e32 v17, 0xbfb8aa3b, v17
	v_add_f32_e32 v18, v110, v8
	v_exp_f32_e32 v17, v17
	v_mul_f32_e32 v18, 0xbfb8aa3b, v18
	v_exp_f32_e32 v18, v18
	v_sub_f32_e32 v13, v52, v49
	v_fma_f32 v15, v13, v5, v49
	v_sub_f32_e32 v13, v54, v53
	v_sub_f32_e32 v16, v56, v55
	v_fma_f32 v13, v13, v4, v53
	v_fma_f32 v19, v16, v7, v55
	v_add_f32_e32 v16, 1.0, v17
	v_rcp_f32_e32 v20, v16
	v_add_f32_e32 v16, 1.0, v18
	v_mul_f32_e32 v21, v13, v6
	v_rcp_f32_e32 v18, v16
	v_mul_f32_e32 v16, v21, v21
	s_nop 1
	v_mov_b32_dpp v16, v16 quad_perm:[1,0,3,2] row_mask:0xf bank_mask:0xf bound_ctrl:1
	v_fmac_f32_e32 v16, v21, v21
	s_nop 1
	v_add_f32_dpp v16, v16, v16 quad_perm:[2,3,0,1] row_mask:0xf bank_mask:0xf bound_ctrl:1
	s_nop 1
	v_add_f32_dpp v16, v16, v16 row_half_mirror row_mask:0xf bank_mask:0xf bound_ctrl:1
	s_nop 1
	v_add_f32_dpp v16, v16, v16 row_mirror row_mask:0xf bank_mask:0xf bound_ctrl:1
	s_nop 0
	v_readlane_b32 s3, v16, 16
	v_readlane_b32 s4, v16, 48
	v_readlane_b32 s0, v16, 0
	v_readlane_b32 s1, v16, 32
	v_mov_b32_e32 v16, s3
	v_mov_b32_e32 v17, s4
	v_pk_add_f32 v[16:17], s[0:1], v[16:17]
	s_nop 0
	v_add_f32_e32 v16, v16, v17
	v_add_f32_e32 v16, 0x2b8cbccc, v16
	v_mul_f32_e32 v17, 0x4b800000, v16
	v_cmp_gt_f32_e64 s[0:1], s91, v16
	s_nop 1
	v_cndmask_b32_e64 v16, v16, v17, s[0:1]
	v_rsq_f32_e32 v16, v16
	v_mul_f32_e32 v17, 0xbf1b4598, v18
	v_mul_f32_e32 v17, 0x3fb8aa3b, v17
	v_exp_f32_e32 v17, v17
	v_mul_f32_e32 v18, 0x45800000, v16
	v_cndmask_b32_e64 v16, v16, v18, s[0:1]
	v_add_f32_e32 v18, -1.0, v20
	v_fma_f32 v18, v3, v18, 1.0
	v_mul_f32_e32 v18, v13, v18
	v_mul_f32_e32 v13, v15, v18
	v_mul_f32_e32 v16, v21, v16
	v_mul_f32_e32 v21, v2, v13
	s_nop 1
	v_mov_b32_dpp v21, v21 quad_perm:[1,0,3,2] row_mask:0xf bank_mask:0xf bound_ctrl:1
	v_fmac_f32_e32 v21, v2, v13
	s_nop 1
	v_add_f32_dpp v13, v21, v21 quad_perm:[2,3,0,1] row_mask:0xf bank_mask:0xf bound_ctrl:1
	v_add_u32_e32 v21, 32, v11
	s_nop 0
	v_add_f32_dpp v13, v13, v13 row_half_mirror row_mask:0xf bank_mask:0xf bound_ctrl:1
	s_nop 1
	v_add_f32_dpp v13, v13, v13 row_mirror row_mask:0xf bank_mask:0xf bound_ctrl:1
	s_nop 0
	v_readlane_b32 s0, v13, 0
	v_readlane_b32 s3, v13, 16
	v_readlane_b32 s1, v13, 32
	v_readlane_b32 s6, v13, 48
	v_mul_f32_e32 v13, v17, v14
	v_rcp_f32_e32 v17, v13
	v_mul_f32_e64 v14, v14, -v16
	v_mul_f32_e32 v15, v15, v13
	ds_write2st64_b32 v21, v14, v15 offset0:2 offset1:70
	v_mul_f32_e32 v14, v20, v16
	v_mul_f32_e32 v14, v17, v14
	v_mul_f32_e32 v15, v18, v17
	ds_write2st64_b32 v21, v14, v15 offset0:138 offset1:206
	ds_write_b32 v12, v19 offset:768
	s_and_saveexec_b64 s[4:5], vcc
	v_mov_b32_e32 v14, s3
	v_mov_b32_e32 v15, s6
	v_pk_add_f32 v[14:15], s[0:1], v[14:15]
	s_nop 0
	v_add_f32_e32 v14, v14, v15
	ds_write_b32 v10, v14 offset:12
	s_or_b64 exec, exec, s[4:5]
	v_add_f32_e32 v15, v66, v9
	v_mul_f32_e32 v15, 0xbfb8aa3b, v15
	v_add_f32_e32 v18, v111, v8
	v_exp_f32_e32 v15, v15
	v_mul_f32_e32 v18, 0xbfb8aa3b, v18
	v_sub_f32_e32 v14, v49, v60
	v_exp_f32_e32 v18, v18
	v_fma_f32 v16, v14, v5, v60
	v_sub_f32_e32 v14, v53, v62
	v_fma_f32 v17, v14, v4, v62
	v_sub_f32_e32 v14, v55, v64
	v_fma_f32 v19, v14, v7, v64
	v_add_f32_e32 v14, 1.0, v15
	v_rcp_f32_e32 v20, v14
	v_add_f32_e32 v14, 1.0, v18
	v_mul_f32_e32 v21, v17, v6
	v_rcp_f32_e32 v18, v14
	v_mul_f32_e32 v14, v21, v21
	s_nop 1
	v_mov_b32_dpp v14, v14 quad_perm:[1,0,3,2] row_mask:0xf bank_mask:0xf bound_ctrl:1
	v_fmac_f32_e32 v14, v21, v21
	s_nop 1
	v_add_f32_dpp v14, v14, v14 quad_perm:[2,3,0,1] row_mask:0xf bank_mask:0xf bound_ctrl:1
	s_nop 1
	v_add_f32_dpp v14, v14, v14 row_half_mirror row_mask:0xf bank_mask:0xf bound_ctrl:1
	s_nop 1
	v_add_f32_dpp v14, v14, v14 row_mirror row_mask:0xf bank_mask:0xf bound_ctrl:1
	s_nop 0
	v_readlane_b32 s3, v14, 16
	v_readlane_b32 s4, v14, 48
	v_readlane_b32 s0, v14, 0
	v_readlane_b32 s1, v14, 32
	v_mov_b32_e32 v14, s3
	v_mov_b32_e32 v15, s4
	v_pk_add_f32 v[14:15], s[0:1], v[14:15]
	s_nop 0
	v_add_f32_e32 v14, v14, v15
	v_add_f32_e32 v14, 0x2b8cbccc, v14
	v_mul_f32_e32 v15, 0x4b800000, v14
	v_cmp_gt_f32_e64 s[0:1], s91, v14
	s_nop 1
	v_cndmask_b32_e64 v14, v14, v15, s[0:1]
	v_rsq_f32_e32 v14, v14
	v_mul_f32_e32 v15, 0xbf1b4598, v18
	v_mul_f32_e32 v15, 0x3fb8aa3b, v15
	v_exp_f32_e32 v15, v15
	v_mul_f32_e32 v18, 0x45800000, v14
	v_cndmask_b32_e64 v14, v14, v18, s[0:1]
	v_mul_f32_e32 v18, v21, v14
	v_add_f32_e32 v14, -1.0, v20
	v_fma_f32 v14, v3, v14, 1.0
	v_mul_f32_e32 v17, v17, v14
	v_mul_f32_e32 v14, v16, v17
	v_mul_f32_e32 v21, v2, v14
	s_nop 1
	v_mov_b32_dpp v21, v21 quad_perm:[1,0,3,2] row_mask:0xf bank_mask:0xf bound_ctrl:1
	v_fmac_f32_e32 v21, v2, v14
	s_nop 1
	v_add_f32_dpp v14, v21, v21 quad_perm:[2,3,0,1] row_mask:0xf bank_mask:0xf bound_ctrl:1
	v_add_u32_e32 v21, 48, v11
	s_nop 0
	v_add_f32_dpp v14, v14, v14 row_half_mirror row_mask:0xf bank_mask:0xf bound_ctrl:1
	s_nop 1
	v_add_f32_dpp v14, v14, v14 row_mirror row_mask:0xf bank_mask:0xf bound_ctrl:1
	s_nop 0
	v_readlane_b32 s0, v14, 0
	v_readlane_b32 s3, v14, 16
	v_readlane_b32 s1, v14, 32
	v_readlane_b32 s6, v14, 48
	v_mul_f32_e32 v14, v15, v13
	v_rcp_f32_e32 v15, v14
	v_mul_f32_e64 v13, v13, -v18
	v_mul_f32_e32 v16, v16, v14
	ds_write2st64_b32 v21, v13, v16 offset0:3 offset1:71
	v_mul_f32_e32 v13, v20, v18
	v_mul_f32_e32 v13, v15, v13
	v_mul_f32_e32 v15, v17, v15
	ds_write2st64_b32 v21, v13, v15 offset0:139 offset1:207
	ds_write_b32 v12, v19 offset:1024
	s_and_saveexec_b64 s[4:5], vcc
	v_mov_b32_e32 v16, s3
	v_mov_b32_e32 v17, s6
	v_pk_add_f32 v[16:17], s[0:1], v[16:17]
	s_nop 0
	v_add_f32_e32 v13, v16, v17
	ds_write_b32 v10, v13 offset:16
	s_or_b64 exec, exec, s[4:5]
	v_add_f32_e32 v17, v65, v9
	v_mul_f32_e32 v17, 0xbfb8aa3b, v17
	v_add_f32_e32 v18, v112, v8
	v_exp_f32_e32 v17, v17
	v_mul_f32_e32 v18, 0xbfb8aa3b, v18
	v_exp_f32_e32 v18, v18
	v_sub_f32_e32 v13, v60, v59
	v_fma_f32 v15, v13, v5, v59
	v_sub_f32_e32 v13, v62, v61
	v_sub_f32_e32 v16, v64, v63
	v_fma_f32 v13, v13, v4, v61
	v_fma_f32 v19, v16, v7, v63
	v_add_f32_e32 v16, 1.0, v17
	v_rcp_f32_e32 v20, v16
	v_add_f32_e32 v16, 1.0, v18
	v_mul_f32_e32 v21, v13, v6
	v_rcp_f32_e32 v18, v16
	v_mul_f32_e32 v16, v21, v21
	s_nop 1
	v_mov_b32_dpp v16, v16 quad_perm:[1,0,3,2] row_mask:0xf bank_mask:0xf bound_ctrl:1
	v_fmac_f32_e32 v16, v21, v21
	s_nop 1
	v_add_f32_dpp v16, v16, v16 quad_perm:[2,3,0,1] row_mask:0xf bank_mask:0xf bound_ctrl:1
	s_nop 1
	v_add_f32_dpp v16, v16, v16 row_half_mirror row_mask:0xf bank_mask:0xf bound_ctrl:1
	s_nop 1
	v_add_f32_dpp v16, v16, v16 row_mirror row_mask:0xf bank_mask:0xf bound_ctrl:1
	s_nop 0
	v_readlane_b32 s3, v16, 16
	v_readlane_b32 s4, v16, 48
	v_readlane_b32 s0, v16, 0
	v_readlane_b32 s1, v16, 32
	v_mov_b32_e32 v16, s3
	v_mov_b32_e32 v17, s4
	v_pk_add_f32 v[16:17], s[0:1], v[16:17]
	s_nop 0
	v_add_f32_e32 v16, v16, v17
	v_add_f32_e32 v16, 0x2b8cbccc, v16
	v_mul_f32_e32 v17, 0x4b800000, v16
	v_cmp_gt_f32_e64 s[0:1], s91, v16
	s_nop 1
	v_cndmask_b32_e64 v16, v16, v17, s[0:1]
	v_rsq_f32_e32 v16, v16
	v_mul_f32_e32 v17, 0xbf1b4598, v18
	v_mul_f32_e32 v17, 0x3fb8aa3b, v17
	v_exp_f32_e32 v17, v17
	v_mul_f32_e32 v18, 0x45800000, v16
	v_cndmask_b32_e64 v16, v16, v18, s[0:1]
	v_add_f32_e32 v18, -1.0, v20
	v_fma_f32 v18, v3, v18, 1.0
	v_mul_f32_e32 v18, v13, v18
	v_mul_f32_e32 v13, v15, v18
	v_mul_f32_e32 v16, v21, v16
	v_mul_f32_e32 v21, v2, v13
	s_nop 1
	v_mov_b32_dpp v21, v21 quad_perm:[1,0,3,2] row_mask:0xf bank_mask:0xf bound_ctrl:1
	v_fmac_f32_e32 v21, v2, v13
	s_nop 1
	v_add_f32_dpp v13, v21, v21 quad_perm:[2,3,0,1] row_mask:0xf bank_mask:0xf bound_ctrl:1
	v_add_u32_e32 v21, 64, v11
	s_nop 0
	v_add_f32_dpp v13, v13, v13 row_half_mirror row_mask:0xf bank_mask:0xf bound_ctrl:1
	s_nop 1
	v_add_f32_dpp v13, v13, v13 row_mirror row_mask:0xf bank_mask:0xf bound_ctrl:1
	s_nop 0
	v_readlane_b32 s0, v13, 0
	v_readlane_b32 s3, v13, 16
	v_readlane_b32 s1, v13, 32
	v_readlane_b32 s6, v13, 48
	v_mul_f32_e32 v13, v17, v14
	v_rcp_f32_e32 v17, v13
	v_mul_f32_e64 v14, v14, -v16
	v_mul_f32_e32 v15, v15, v13
	ds_write2st64_b32 v21, v14, v15 offset0:4 offset1:72
	v_mul_f32_e32 v14, v20, v16
	v_mul_f32_e32 v14, v17, v14
	v_mul_f32_e32 v15, v18, v17
	ds_write2st64_b32 v21, v14, v15 offset0:140 offset1:208
	ds_write_b32 v12, v19 offset:1280
	s_and_saveexec_b64 s[4:5], vcc
	v_mov_b32_e32 v14, s3
	v_mov_b32_e32 v15, s6
	v_pk_add_f32 v[14:15], s[0:1], v[14:15]
	s_nop 0
	v_add_f32_e32 v14, v14, v15
	ds_write_b32 v10, v14 offset:20
	s_or_b64 exec, exec, s[4:5]
	v_add_f32_e32 v15, v74, v9
	v_mul_f32_e32 v15, 0xbfb8aa3b, v15
	v_add_f32_e32 v18, v113, v8
	v_exp_f32_e32 v15, v15
	v_mul_f32_e32 v18, 0xbfb8aa3b, v18
	v_sub_f32_e32 v14, v59, v67
	v_exp_f32_e32 v18, v18
	v_fma_f32 v16, v14, v5, v67
	v_sub_f32_e32 v14, v61, v69
	v_fma_f32 v17, v14, v4, v69
	v_sub_f32_e32 v14, v63, v71
	v_fma_f32 v19, v14, v7, v71
	v_add_f32_e32 v14, 1.0, v15
	v_rcp_f32_e32 v20, v14
	v_add_f32_e32 v14, 1.0, v18
	v_mul_f32_e32 v21, v17, v6
	v_rcp_f32_e32 v18, v14
	v_mul_f32_e32 v14, v21, v21
	s_nop 1
	v_mov_b32_dpp v14, v14 quad_perm:[1,0,3,2] row_mask:0xf bank_mask:0xf bound_ctrl:1
	v_fmac_f32_e32 v14, v21, v21
	s_nop 1
	v_add_f32_dpp v14, v14, v14 quad_perm:[2,3,0,1] row_mask:0xf bank_mask:0xf bound_ctrl:1
	s_nop 1
	v_add_f32_dpp v14, v14, v14 row_half_mirror row_mask:0xf bank_mask:0xf bound_ctrl:1
	s_nop 1
	v_add_f32_dpp v14, v14, v14 row_mirror row_mask:0xf bank_mask:0xf bound_ctrl:1
	s_nop 0
	v_readlane_b32 s3, v14, 16
	v_readlane_b32 s4, v14, 48
	v_readlane_b32 s0, v14, 0
	v_readlane_b32 s1, v14, 32
	v_mov_b32_e32 v14, s3
	v_mov_b32_e32 v15, s4
	v_pk_add_f32 v[14:15], s[0:1], v[14:15]
	s_nop 0
	v_add_f32_e32 v14, v14, v15
	v_add_f32_e32 v14, 0x2b8cbccc, v14
	v_mul_f32_e32 v15, 0x4b800000, v14
	v_cmp_gt_f32_e64 s[0:1], s91, v14
	s_nop 1
	v_cndmask_b32_e64 v14, v14, v15, s[0:1]
	v_rsq_f32_e32 v14, v14
	v_mul_f32_e32 v15, 0xbf1b4598, v18
	v_mul_f32_e32 v15, 0x3fb8aa3b, v15
	v_exp_f32_e32 v15, v15
	v_mul_f32_e32 v18, 0x45800000, v14
	v_cndmask_b32_e64 v14, v14, v18, s[0:1]
	v_mul_f32_e32 v18, v21, v14
	v_add_f32_e32 v14, -1.0, v20
	v_fma_f32 v14, v3, v14, 1.0
	v_mul_f32_e32 v17, v17, v14
	v_mul_f32_e32 v14, v16, v17
	v_mul_f32_e32 v21, v2, v14
	s_nop 1
	v_mov_b32_dpp v21, v21 quad_perm:[1,0,3,2] row_mask:0xf bank_mask:0xf bound_ctrl:1
	v_fmac_f32_e32 v21, v2, v14
	s_nop 1
	v_add_f32_dpp v14, v21, v21 quad_perm:[2,3,0,1] row_mask:0xf bank_mask:0xf bound_ctrl:1
	v_add_u32_e32 v21, 0x50, v11
	s_nop 0
	v_add_f32_dpp v14, v14, v14 row_half_mirror row_mask:0xf bank_mask:0xf bound_ctrl:1
	s_nop 1
	v_add_f32_dpp v14, v14, v14 row_mirror row_mask:0xf bank_mask:0xf bound_ctrl:1
	s_nop 0
	v_readlane_b32 s0, v14, 0
	v_readlane_b32 s3, v14, 16
	v_readlane_b32 s1, v14, 32
	v_readlane_b32 s6, v14, 48
	v_mul_f32_e32 v14, v15, v13
	v_rcp_f32_e32 v15, v14
	v_mul_f32_e64 v13, v13, -v18
	v_mul_f32_e32 v16, v16, v14
	ds_write2st64_b32 v21, v13, v16 offset0:5 offset1:73
	v_mul_f32_e32 v13, v20, v18
	v_mul_f32_e32 v13, v15, v13
	v_mul_f32_e32 v15, v17, v15
	ds_write2st64_b32 v21, v13, v15 offset0:141 offset1:209
	ds_write_b32 v12, v19 offset:1536
	s_and_saveexec_b64 s[4:5], vcc
	v_mov_b32_e32 v16, s3
	v_mov_b32_e32 v17, s6
	v_pk_add_f32 v[16:17], s[0:1], v[16:17]
	s_nop 0
	v_add_f32_e32 v13, v16, v17
	ds_write_b32 v10, v13 offset:24
	s_or_b64 exec, exec, s[4:5]
	v_sub_f32_e32 v13, v67, v68
	v_fma_f32 v13, v13, v5, v68
	v_sub_f32_e32 v5, v69, v70
	v_fma_f32 v15, v5, v4, v70
	v_add_f32_e32 v5, v73, v9
	v_mul_f32_e32 v5, 0xbfb8aa3b, v5
	v_add_f32_e32 v8, v114, v8
	v_exp_f32_e32 v5, v5
	v_mul_f32_e32 v8, 0xbfb8aa3b, v8
	v_exp_f32_e32 v8, v8
	v_sub_f32_e32 v4, v71, v72
	v_fma_f32 v7, v4, v7, v72
	v_add_f32_e32 v4, 1.0, v5
	v_rcp_f32_e32 v9, v4
	v_add_f32_e32 v4, 1.0, v8
	v_mul_f32_e32 v6, v15, v6
	v_rcp_f32_e32 v8, v4
	v_mul_f32_e32 v4, v6, v6
	v_add_u32_e32 v11, 0x60, v11
	s_nop 0
	v_mov_b32_dpp v4, v4 quad_perm:[1,0,3,2] row_mask:0xf bank_mask:0xf bound_ctrl:1
	v_fmac_f32_e32 v4, v6, v6
	s_nop 1
	v_add_f32_dpp v4, v4, v4 quad_perm:[2,3,0,1] row_mask:0xf bank_mask:0xf bound_ctrl:1
	s_nop 1
	v_add_f32_dpp v4, v4, v4 row_half_mirror row_mask:0xf bank_mask:0xf bound_ctrl:1
	s_nop 1
	v_add_f32_dpp v4, v4, v4 row_mirror row_mask:0xf bank_mask:0xf bound_ctrl:1
	s_nop 0
	v_readlane_b32 s3, v4, 16
	v_readlane_b32 s4, v4, 48
	v_readlane_b32 s0, v4, 0
	v_readlane_b32 s1, v4, 32
	v_mov_b32_e32 v4, s3
	v_mov_b32_e32 v5, s4
	v_pk_add_f32 v[4:5], s[0:1], v[4:5]
	s_nop 0
	v_add_f32_e32 v4, v4, v5
	v_add_f32_e32 v4, 0x2b8cbccc, v4
	v_mul_f32_e32 v5, 0x4b800000, v4
	v_cmp_gt_f32_e64 s[0:1], s91, v4
	s_nop 1
	v_cndmask_b32_e64 v4, v4, v5, s[0:1]
	v_rsq_f32_e32 v4, v4
	v_mul_f32_e32 v5, 0xbf1b4598, v8
	v_mul_f32_e32 v5, 0x3fb8aa3b, v5
	v_exp_f32_e32 v5, v5
	v_mul_f32_e32 v8, 0x45800000, v4
	v_cndmask_b32_e64 v4, v4, v8, s[0:1]
	v_mul_f32_e32 v4, v6, v4
	v_add_f32_e32 v6, -1.0, v9
	v_fma_f32 v3, v3, v6, 1.0
	v_mul_f32_e32 v3, v15, v3
	v_mul_f32_e32 v6, v13, v3
	v_mul_f32_e32 v8, v2, v6
	s_nop 1
	v_mov_b32_dpp v8, v8 quad_perm:[1,0,3,2] row_mask:0xf bank_mask:0xf bound_ctrl:1
	v_fmac_f32_e32 v8, v2, v6
	v_mul_f32_e64 v6, v14, -v4
	v_mul_f32_e32 v4, v9, v4
	v_add_f32_dpp v2, v8, v8 quad_perm:[2,3,0,1] row_mask:0xf bank_mask:0xf bound_ctrl:1
	s_nop 1
	v_add_f32_dpp v2, v2, v2 row_half_mirror row_mask:0xf bank_mask:0xf bound_ctrl:1
	s_nop 1
	v_add_f32_dpp v2, v2, v2 row_mirror row_mask:0xf bank_mask:0xf bound_ctrl:1
	s_nop 0
	v_readlane_b32 s0, v2, 0
	v_readlane_b32 s3, v2, 16
	v_readlane_b32 s1, v2, 32
	v_readlane_b32 s6, v2, 48
	v_mul_f32_e32 v2, v5, v14
	v_rcp_f32_e32 v5, v2
	v_mul_f32_e32 v8, v13, v2
	ds_write2st64_b32 v11, v6, v8 offset0:6 offset1:74
	v_mul_f32_e32 v4, v5, v4
	v_mul_f32_e32 v3, v3, v5
	ds_write2st64_b32 v11, v4, v3 offset0:142 offset1:210
	ds_write_b32 v12, v7 offset:1792
	s_and_saveexec_b64 s[4:5], vcc
	v_mov_b32_e32 v4, s3
	v_mov_b32_e32 v5, s6
	v_pk_add_f32 v[4:5], s[0:1], v[4:5]
	s_nop 0
	v_add_f32_e32 v3, v4, v5
	ds_write_b32 v10, v3 offset:28
	s_or_b64 exec, exec, s[4:5]
	v_lshlrev_b32_e32 v3, 8, v78
	v_lshlrev_b32_e32 v4, 2, v76
	v_add3_u32 v3, s92, v3, v4
	ds_write_b32 v3, v2
	v_and_b32_e32 v124, 15, v76
	v_lshrrev_b32_e32 v125, 4, v76
	v_and_b32_e32 v132, 7, v124
	v_add_u32_e32 v126, v26, v132
	v_mul_u32_u24_e32 v126, 0x110, v126
	v_lshl_add_u32 v126, v125, 4, v126
	v_and_b32_e32 v127, 8, v124
	v_mul_u32_u24_e32 v127, 0x880, v127
	v_add_u32_e32 v128, v126, v127
	v_add_u32_e32 v129, 0x8800, v128
	ds_read_b128 v[136:139], v128 offset:0
	ds_read_b128 v[152:155], v129 offset:0
	ds_read_b128 v[140:143], v128 offset:64
	ds_read_b128 v[156:159], v129 offset:64
	ds_read_b128 v[144:147], v128 offset:128
	ds_read_b128 v[160:163], v129 offset:128
	ds_read_b128 v[148:151], v128 offset:192
	ds_read_b128 v[164:167], v129 offset:192
	v_lshrrev_b32_e32 v126, 1, v125
	v_lshrrev_b32_e32 v127, 3, v124
	v_lshl_add_u32 v127, v126, 1, v127
	v_lshlrev_b32_e32 v130, 8, v127
	v_lshl_add_u32 v130, v26, 7, v130
	v_and_b32_e32 v127, 1, v125
	v_lshl_add_u32 v130, v127, 7, v130
	v_lshl_add_u32 v130, v132, 2, v130
	v_add_u32_e32 v130, 0x15800, v130
	v_sub_u32_e32 v131, 1, v126
	v_add_u32_e32 v131, v131, v132
	v_lshlrev_b32_e32 v127, 2, v127
	v_sub_u32_e32 v131, v131, v127
	v_max_i32_e32 v131, 0, v131
	v_cmp_ge_u32_e64 s[0:1], 1, v131
	v_cmp_ge_u32_e64 s[4:5], 2, v131
	v_cmp_ge_u32_e64 s[6:7], 3, v131
	v_cmp_ge_u32_e32 vcc, 0, v131
	s_waitcnt lgkmcnt(0)
	v_mfma_f32_16x16x4_f32 v[36:39], v136, v152, 0
	v_mfma_f32_16x16x4_f32 v[40:43], v137, v153, 0
	v_mfma_f32_16x16x4_f32 v[36:39], v138, v154, v[36:39]
	v_mfma_f32_16x16x4_f32 v[40:43], v139, v155, v[40:43]
	v_mfma_f32_16x16x4_f32 v[36:39], v140, v156, v[36:39]
	v_mfma_f32_16x16x4_f32 v[40:43], v141, v157, v[40:43]
	v_mfma_f32_16x16x4_f32 v[36:39], v142, v158, v[36:39]
	v_mfma_f32_16x16x4_f32 v[40:43], v143, v159, v[40:43]
	v_mfma_f32_16x16x4_f32 v[36:39], v144, v160, v[36:39]
	v_mfma_f32_16x16x4_f32 v[40:43], v145, v161, v[40:43]
	v_mfma_f32_16x16x4_f32 v[36:39], v146, v162, v[36:39]
	v_mfma_f32_16x16x4_f32 v[40:43], v147, v163, v[40:43]
	v_mfma_f32_16x16x4_f32 v[36:39], v148, v164, v[36:39]
	v_mfma_f32_16x16x4_f32 v[40:43], v149, v165, v[40:43]
	v_mfma_f32_16x16x4_f32 v[36:39], v150, v166, v[36:39]
	v_mfma_f32_16x16x4_f32 v[40:43], v151, v167, v[40:43]
	s_nop 7
	s_nop 2
	v_pk_add_f32 v[36:37], v[36:37], v[40:41]
	v_pk_add_f32 v[38:39], v[38:39], v[42:43]
	v_cndmask_b32_e32 v36, 0, v36, vcc
	v_cndmask_b32_e64 v37, 0, v37, s[0:1]
	v_cndmask_b32_e64 v38, 0, v38, s[4:5]
	v_cndmask_b32_e64 v39, 0, v39, s[6:7]
	ds_write_b32 v130, v36 offset:0
	ds_write_b32 v130, v37 offset:32
	ds_write_b32 v130, v38 offset:64
	ds_write_b32 v130, v39 offset:96
	s_lshl_b32 s17, s40, 6
	s_cmp_lg_u32 s40, 31
	s_waitcnt lgkmcnt(0)
	s_barrier
	s_cbranch_scc0 .LBB0_586
	s_add_i32 s3, s17, 64
	s_add_u32 s0, s80, s3
	s_addc_u32 s1, s81, 0
	v_ashrrev_i32_e32 v27, 31, v26
	v_lshl_add_u64 v[4:5], s[0:1], 0, v[26:27]
	v_mad_u64_u32 v[2:3], s[0:1], v4, s83, 0
	v_mad_i32_i24 v3, v5, s83, v3
	v_add_u32_e32 v1, s3, v26
	v_mov_b32_e32 v95, v94
	v_lshl_add_u64 v[2:3], s[46:47], 0, v[2:3]
	v_cmp_lt_i32_e32 vcc, 0, v1
	v_mov_b32_e32 v106, 0
	v_lshl_add_u64 v[2:3], v[28:29], 1, v[2:3]
	v_mov_b64_e32 v[34:35], v[94:95]
	s_and_saveexec_b64 s[0:1], vcc
	s_cbranch_execz .LBB0_585
	global_load_ushort v52, v[2:3], off offset:-3072
	global_load_ushort v53, v[2:3], off offset:-2048
	global_load_ushort v54, v[2:3], off offset:-1024
